# C item xhatT LDS image: chunk swizzle also XORs (channel>>6)<<1 so the four channel-quarter lanes of a token write different banks (transposition writes 4-way -> conflict-free), reader addresses adjus
# baseline (speedup 1.0000x reference)
.LBB0_779:
	v_mov_b32_e32 v43, v0
	s_ashr_i32 s5, s3, 31
	v_ashrrev_i32_e32 v44, 7, v43
	s_waitcnt vmcnt(2)
	v_add_u32_e32 v164, s2, v44
	v_ashrrev_i32_e32 v165, 31, v164
	v_and_b32_e32 v168, 31, v43
	s_waitcnt vmcnt(0)
	v_lshlrev_b64 v[2:3], 15, v[164:165]
	v_bfe_u32 v169, v43, 5, 1
	v_lshl_add_u64 v[2:3], s[56:57], 0, v[2:3]
	v_and_b32_e32 v18, 63, v43
	v_lshlrev_b32_e32 v18, 4, v18
	v_lshlrev_b32_e32 v154, 4, v169
	v_add_u32_e32 v18, 0x1000, v18
	v_add_co_u32_e32 v18, vcc, v2, v18
	s_nop 1
	v_addc_co_u32_e32 v19, vcc, 0, v3, vcc
	v_add_co_u32_e32 v20, vcc, s14, v18
	v_ashrrev_i32_e32 v45, 2, v43
	s_nop 0
	v_addc_co_u32_e32 v21, vcc, 0, v19, vcc
	v_add_co_u32_e32 v22, vcc, s17, v18
	global_load_dwordx4 v[2:5], v[18:19], off offset:-4096
	global_load_dwordx4 v[6:9], v[20:21], off offset:-4096
	v_addc_co_u32_e32 v23, vcc, 0, v19, vcc
	v_add_co_u32_e32 v24, vcc, s30, v18
	global_load_dwordx4 v[10:13], v[22:23], off offset:-4096
	s_nop 0
	v_addc_co_u32_e32 v25, vcc, 0, v19, vcc
	global_load_dwordx4 v[14:17], v[24:25], off offset:-4096
	global_load_dwordx4 v[138:141], v[18:19], off offset:-3072
	global_load_dwordx4 v[142:145], v[20:21], off offset:-3072
	global_load_dwordx4 v[146:149], v[22:23], off offset:-3072
	global_load_dwordx4 v[150:153], v[24:25], off offset:-3072
	global_load_dwordx4 v[126:129], v[20:21], off offset:-2048
	global_load_dwordx4 v[130:133], v[22:23], off offset:-2048
	global_load_dwordx4 v[134:137], v[24:25], off offset:-2048
	global_load_dwordx4 v[114:117], v[20:21], off offset:-1024
	global_load_dwordx4 v[118:121], v[22:23], off offset:-1024
	global_load_dwordx4 v[122:125], v[24:25], off offset:-1024
	global_load_dwordx4 v[106:109], v[22:23], off
	global_load_dwordx4 v[110:113], v[24:25], off
	global_load_dwordx4 v[98:101], v[22:23], off offset:1024
	global_load_dwordx4 v[102:105], v[24:25], off offset:1024
	global_load_dwordx4 v[94:97], v[24:25], off offset:2048
	global_load_dwordx4 v[90:93], v[24:25], off offset:3072
	v_add_u32_e32 v18, s3, v45
	v_ashrrev_i32_e32 v19, 31, v18
	v_lshlrev_b32_e32 v20, 6, v43
	v_lshlrev_b64 v[18:19], 12, v[18:19]
	v_and_b32_e32 v46, 0xc0, v20
	v_lshl_add_u64 v[18:19], s[60:61], 0, v[18:19]
	v_lshlrev_b32_e32 v20, 1, v46
	v_mov_b32_e32 v21, v155
	v_lshl_add_u64 v[34:35], v[18:19], 0, v[20:21]
	global_load_dwordx4 v[18:21], v[34:35], off offset:3632
	global_load_dwordx4 v[22:25], v[34:35], off offset:3616
	global_load_dwordx4 v[26:29], v[34:35], off offset:3600
	global_load_dwordx4 v[30:33], v[34:35], off offset:3584
	global_load_dwordx4 v[36:39], v[34:35], off offset:3680
	global_load_dwordx4 v[202:205], v[34:35], off offset:3664
	global_load_dwordx4 v[48:51], v[34:35], off offset:3648
	global_load_dwordx4 v[206:209], v[34:35], off offset:3696
	v_lshrrev_b32_e32 v42, 5, v43
	s_add_i32 s4, s4, s46
	s_waitcnt vmcnt(7)
	v_lshlrev_b32_e32 v178, 16, v18
	s_waitcnt vmcnt(6)
	v_lshlrev_b32_e32 v186, 16, v22
	s_waitcnt vmcnt(5)
	v_lshlrev_b32_e32 v194, 16, v26
	s_waitcnt vmcnt(4)
	v_lshlrev_b32_e32 v200, 16, v30
	v_and_b32_e32 v199, 0xffff0000, v30
	v_add_f32_e32 v30, 0, v200
	v_lshlrev_b32_e32 v198, 16, v31
	v_add_f32_e32 v30, v30, v199
	v_and_b32_e32 v197, 0xffff0000, v31
	v_mul_f32_e32 v31, v199, v199
	v_add_f32_e32 v30, v30, v198
	v_lshlrev_b32_e32 v196, 16, v32
	v_fmac_f32_e32 v31, v200, v200
	v_add_f32_e32 v30, v30, v197
	v_and_b32_e32 v195, 0xffff0000, v32
	v_fmac_f32_e32 v31, v198, v198
	v_add_f32_e32 v30, v30, v196
	v_lshlrev_b32_e32 v193, 16, v33
	v_fmac_f32_e32 v31, v197, v197
	v_add_f32_e32 v30, v30, v195
	v_and_b32_e32 v191, 0xffff0000, v33
	v_fmac_f32_e32 v31, v196, v196
	v_add_f32_e32 v30, v30, v193
	v_fmac_f32_e32 v31, v195, v195
	v_add_f32_e32 v30, v30, v191
	v_fmac_f32_e32 v31, v193, v193
	v_and_b32_e32 v192, 0xffff0000, v26
	v_add_f32_e32 v26, v30, v194
	v_fmac_f32_e32 v31, v191, v191
	v_lshlrev_b32_e32 v190, 16, v27
	v_add_f32_e32 v26, v26, v192
	v_and_b32_e32 v189, 0xffff0000, v27
	v_fmac_f32_e32 v31, v194, v194
	v_add_f32_e32 v26, v26, v190
	v_lshlrev_b32_e32 v188, 16, v28
	v_fmac_f32_e32 v31, v192, v192
	v_add_f32_e32 v26, v26, v189
	v_and_b32_e32 v187, 0xffff0000, v28
	v_fmac_f32_e32 v31, v190, v190
	v_add_f32_e32 v26, v26, v188
	v_lshlrev_b32_e32 v184, 16, v29
	v_fmac_f32_e32 v31, v189, v189
	v_add_f32_e32 v26, v26, v187
	v_and_b32_e32 v182, 0xffff0000, v29
	v_fmac_f32_e32 v31, v188, v188
	v_add_f32_e32 v26, v26, v184
	v_fmac_f32_e32 v31, v187, v187
	v_add_f32_e32 v26, v26, v182
	v_fmac_f32_e32 v31, v184, v184
	v_and_b32_e32 v185, 0xffff0000, v22
	v_add_f32_e32 v22, v26, v186
	v_fmac_f32_e32 v31, v182, v182
	v_lshlrev_b32_e32 v183, 16, v23
	v_add_f32_e32 v22, v22, v185
	v_and_b32_e32 v179, 0xffff0000, v23
	v_fmac_f32_e32 v31, v186, v186
	v_add_f32_e32 v22, v22, v183
	v_lshlrev_b32_e32 v177, 16, v24
	v_fmac_f32_e32 v31, v185, v185
	v_add_f32_e32 v22, v22, v179
	v_and_b32_e32 v175, 0xffff0000, v24
	v_fmac_f32_e32 v31, v183, v183
	v_add_f32_e32 v22, v22, v177
	v_lshlrev_b32_e32 v173, 16, v25
	v_fmac_f32_e32 v31, v179, v179
	v_add_f32_e32 v22, v22, v175
	v_and_b32_e32 v171, 0xffff0000, v25
	v_fmac_f32_e32 v31, v177, v177
	v_add_f32_e32 v22, v22, v173
	v_fmac_f32_e32 v31, v175, v175
	v_add_f32_e32 v22, v22, v171
	v_fmac_f32_e32 v31, v173, v173
	v_and_b32_e32 v176, 0xffff0000, v18
	v_add_f32_e32 v18, v22, v178
	v_fmac_f32_e32 v31, v171, v171
	v_lshlrev_b32_e32 v174, 16, v19
	v_add_f32_e32 v18, v18, v176
	v_and_b32_e32 v172, 0xffff0000, v19
	v_fmac_f32_e32 v31, v178, v178
	v_add_f32_e32 v18, v18, v174
	v_lshlrev_b32_e32 v167, 16, v20
	v_fmac_f32_e32 v31, v176, v176
	v_add_f32_e32 v18, v18, v172
	v_and_b32_e32 v165, 0xffff0000, v20
	v_fmac_f32_e32 v31, v174, v174
	v_add_f32_e32 v18, v18, v167
	v_lshlrev_b32_e32 v64, 16, v21
	v_fmac_f32_e32 v31, v172, v172
	v_add_f32_e32 v18, v18, v165
	v_and_b32_e32 v62, 0xffff0000, v21
	v_fmac_f32_e32 v31, v167, v167
	v_add_f32_e32 v18, v18, v64
	v_fmac_f32_e32 v31, v165, v165
	v_add_f32_e32 v18, v18, v62
	s_waitcnt vmcnt(1)
	v_lshlrev_b32_e32 v170, 16, v48
	v_fmac_f32_e32 v31, v64, v64
	v_and_b32_e32 v166, 0xffff0000, v48
	v_add_f32_e32 v18, v18, v170
	v_fmac_f32_e32 v31, v62, v62
	v_lshlrev_b32_e32 v65, 16, v49
	v_add_f32_e32 v18, v18, v166
	v_and_b32_e32 v63, 0xffff0000, v49
	v_fmac_f32_e32 v31, v170, v170
	v_add_f32_e32 v18, v18, v65
	v_lshlrev_b32_e32 v60, 16, v50
	v_fmac_f32_e32 v31, v166, v166
	v_add_f32_e32 v18, v18, v63
	v_and_b32_e32 v59, 0xffff0000, v50
	v_fmac_f32_e32 v31, v65, v65
	v_add_f32_e32 v18, v18, v60
	v_lshlrev_b32_e32 v57, 16, v51
	v_fmac_f32_e32 v31, v63, v63
	v_add_f32_e32 v18, v18, v59
	v_and_b32_e32 v55, 0xffff0000, v51
	v_fmac_f32_e32 v31, v60, v60
	v_add_f32_e32 v18, v18, v57
	v_fmac_f32_e32 v31, v59, v59
	v_add_f32_e32 v18, v18, v55
	v_lshlrev_b32_e32 v61, 16, v202
	v_fmac_f32_e32 v31, v57, v57
	v_and_b32_e32 v58, 0xffff0000, v202
	v_add_f32_e32 v18, v18, v61
	v_fmac_f32_e32 v31, v55, v55
	v_lshlrev_b32_e32 v56, 16, v203
	v_add_f32_e32 v18, v18, v58
	v_and_b32_e32 v54, 0xffff0000, v203
	v_fmac_f32_e32 v31, v61, v61
	v_add_f32_e32 v18, v18, v56
	v_lshlrev_b32_e32 v53, 16, v204
	v_fmac_f32_e32 v31, v58, v58
	v_add_f32_e32 v18, v18, v54
	v_and_b32_e32 v51, 0xffff0000, v204
	v_fmac_f32_e32 v31, v56, v56
	v_add_f32_e32 v18, v18, v53
	v_lshlrev_b32_e32 v49, 16, v205
	v_fmac_f32_e32 v31, v54, v54
	v_add_f32_e32 v18, v18, v51
	v_and_b32_e32 v47, 0xffff0000, v205
	v_fmac_f32_e32 v31, v53, v53
	v_add_f32_e32 v18, v18, v49
	v_fmac_f32_e32 v31, v51, v51
	v_add_f32_e32 v18, v18, v47
	v_lshlrev_b32_e32 v52, 16, v36
	v_fmac_f32_e32 v31, v49, v49
	v_and_b32_e32 v50, 0xffff0000, v36
	v_add_f32_e32 v18, v18, v52
	v_fmac_f32_e32 v31, v47, v47
	v_lshlrev_b32_e32 v48, 16, v37
	v_add_f32_e32 v18, v18, v50
	v_fmac_f32_e32 v31, v52, v52
	v_add_f32_e32 v18, v18, v48
	v_and_b32_e32 v37, 0xffff0000, v37
	v_fmac_f32_e32 v31, v50, v50
	v_lshlrev_b32_e32 v34, 16, v38
	v_mov_b32_e32 v35, v37
	v_add_f32_e32 v20, v18, v37
	v_fmac_f32_e32 v31, v48, v48
	v_and_b32_e32 v24, 0xffff0000, v38
	v_pk_mul_f32 v[18:19], v[34:35], v[34:35]
	v_add_f32_e32 v20, v20, v34
	v_lshlrev_b32_e32 v25, 16, v39
	v_add_f32_e32 v19, v19, v31
	v_add_f32_e32 v20, v20, v24
	v_add_f32_e32 v21, v18, v19
	v_pk_mul_f32 v[18:19], v[24:25], v[24:25]
	v_add_f32_e32 v20, v20, v25
	v_and_b32_e32 v33, 0xffff0000, v39
	v_add_f32_e32 v18, v18, v21
	s_waitcnt vmcnt(0)
	v_lshlrev_b32_e32 v28, 16, v206
	v_mov_b32_e32 v29, v33
	v_add_f32_e32 v20, v20, v33
	v_add_f32_e32 v21, v19, v18
	v_and_b32_e32 v22, 0xffff0000, v206
	v_pk_mul_f32 v[18:19], v[28:29], v[28:29]
	v_add_f32_e32 v20, v20, v28
	v_lshlrev_b32_e32 v23, 16, v207
	v_add_f32_e32 v19, v19, v21
	v_add_f32_e32 v20, v20, v22
	v_add_f32_e32 v21, v18, v19
	v_pk_mul_f32 v[18:19], v[22:23], v[22:23]
	v_add_f32_e32 v29, v20, v23
	v_and_b32_e32 v31, 0xffff0000, v207
	v_add_f32_e32 v18, v18, v21
	v_lshlrev_b32_e32 v26, 16, v208
	v_mov_b32_e32 v27, v31
	v_add_f32_e32 v29, v29, v31
	v_and_b32_e32 v36, s0, v38
	v_add_f32_e32 v18, v19, v18
	v_and_b32_e32 v20, 0xffff0000, v208
	v_pk_mul_f32 v[38:39], v[26:27], v[26:27]
	v_add_f32_e32 v27, v29, v26
	v_lshlrev_b32_e32 v21, 16, v209
	v_add_f32_e32 v18, v39, v18
	v_add_f32_e32 v27, v27, v20
	v_and_b32_e32 v29, 64, v181
	v_add_f32_e32 v18, v38, v18
	v_pk_mul_f32 v[40:41], v[20:21], v[20:21]
	v_add_f32_e32 v39, v27, v21
	v_xor_b32_e32 v27, 1, v181
	v_add_u32_e32 v29, 64, v29
	v_and_b32_e32 v19, 0xffff0000, v209
	v_add_f32_e32 v18, v40, v18
	v_cmp_lt_i32_e32 vcc, v27, v29
	v_add_f32_e32 v18, v41, v18
	v_mul_f32_e32 v38, v19, v19
	v_cndmask_b32_e32 v27, v181, v27, vcc
	v_lshlrev_b32_e32 v27, 2, v27
	v_pk_add_f32 v[38:39], v[38:39], v[18:19]
	s_nop 1
	v_mov_b32_dpp v41, v39 quad_perm:[1,0,3,2] row_mask:0xf bank_mask:0xf
	v_mov_b32_dpp v40, v38 quad_perm:[1,0,3,2] row_mask:0xf bank_mask:0xf
	v_xor_b32_e32 v35, 2, v181
	v_cmp_lt_i32_e32 vcc, v35, v29
	v_and_b32_e32 v30, s0, v206
	v_mov_b32_e32 v32, v36
	v_cndmask_b32_e32 v29, v181, v35, vcc
	v_lshlrev_b32_e32 v29, 2, v29
	s_waitcnt lgkmcnt(0)
	v_pk_add_f32 v[38:39], v[38:39], v[40:41]
	s_nop 1
	v_mov_b32_dpp v41, v39 quad_perm:[2,3,0,1] row_mask:0xf bank_mask:0xf
	v_mov_b32_dpp v40, v38 quad_perm:[2,3,0,1] row_mask:0xf bank_mask:0xf
	s_waitcnt lgkmcnt(0)
	v_pk_add_f32 v[40:41], v[38:39], v[40:41]
	s_nop 0
	v_pk_mul_f32 v[38:39], v[40:41], s[22:23] op_sel_hi:[1,0]
	v_pk_fma_f32 v[36:37], v[40:41], s[22:23], v[36:37] op_sel_hi:[1,0,1] neg_lo:[1,0,0] neg_hi:[1,0,0]
	v_fma_f32 v18, -v39, v39, v38
	v_max_f32_e32 v18, 0, v18
	v_add_f32_e32 v18, 0x358637bd, v18
	v_cmp_gt_f32_e32 vcc, s33, v18
	v_mul_f32_e32 v27, 0x4b800000, v18
	v_sub_f32_e32 v29, v200, v39
	v_cndmask_b32_e32 v18, v18, v27, vcc
	v_rsq_f32_e32 v18, v18
	v_sub_f32_e32 v19, v19, v39
	v_mul_f32_e32 v27, 0x45800000, v18
	v_cndmask_b32_e32 v18, v18, v27, vcc
	v_mul_f32_e32 v29, v29, v18
	v_lshlrev_b32_e32 v27, 1, v45
	v_bfe_u32 v35, v29, 16, 1
	v_ashrrev_i32_e32 v45, 1, v43
	v_and_b32_e32 v216, 3, v43
	v_lshlrev_b32_e32 v216, 5, v216
	v_xor_b32_e32 v45, v216, v45
	v_and_b32_e32 v27, 14, v27
	v_add3_u32 v29, v29, v35, s15
	v_lshl_add_u32 v35, v46, 8, 32
	v_and_b32_e32 v46, -16, v45
	v_add3_u32 v200, v35, v46, v27
	ds_write_b16_d16_hi v200, v29 offset:55296
	v_mul_f32_e64 v215, -v39, v18
	v_fma_f32 v29, v199, v18, v215
	v_cvt_pk_bf16_f32 v29, v29, v29
	v_bitop3_b32 v199, v45, 16, -16 bitop3:0x6c
	v_add3_u32 v201, v35, v199, v27
	ds_write_b16 v201, v29 offset:55552
	v_fma_f32 v29, v198, v18, v215
	v_cvt_pk_bf16_f32 v29, v29, v29
	v_bitop3_b32 v198, v45, 32, -16 bitop3:0x6c
	v_add3_u32 v202, v35, v198, v27
	ds_write_b16 v202, v29 offset:55808
	v_fma_f32 v29, v197, v18, v215
	v_cvt_pk_bf16_f32 v29, v29, v29
	v_bitop3_b32 v197, v45, 48, -16 bitop3:0x6c
	v_add3_u32 v203, v35, v197, v27
	ds_write_b16 v203, v29 offset:56064
	v_fma_f32 v29, v196, v18, v215
	v_cvt_pk_bf16_f32 v29, v29, v29
	v_bitop3_b32 v196, v45, 64, -16 bitop3:0x6c
	v_add3_u32 v204, v35, v196, v27
	ds_write_b16 v204, v29 offset:56320
	v_fma_f32 v29, v195, v18, v215
	v_cvt_pk_bf16_f32 v29, v29, v29
	v_bitop3_b32 v195, v45, s34, -16 bitop3:0x6c
	v_add3_u32 v205, v35, v195, v27
	ds_write_b16 v205, v29 offset:56576
	v_fma_f32 v29, v193, v18, v215
	v_cvt_pk_bf16_f32 v29, v29, v29
	v_bitop3_b32 v193, v45, s31, -16 bitop3:0x6c
	v_add3_u32 v206, v35, v193, v27
	ds_write_b16 v206, v29 offset:56832
	v_fma_f32 v29, v191, v18, v215
	v_cvt_pk_bf16_f32 v29, v29, v29
	v_bitop3_b32 v191, v45, s13, -16 bitop3:0x6c
	v_add3_u32 v207, v35, v191, v27
	ds_write_b16 v207, v29 offset:57088
	v_fma_f32 v29, v194, v18, v215
	v_cvt_pk_bf16_f32 v29, v29, v29
	v_bitop3_b32 v194, v45, s12, -16 bitop3:0x6c
	v_add3_u32 v208, v35, v194, v27
	ds_write_b16 v208, v29 offset:57344
	v_fma_f32 v29, v192, v18, v215
	v_cvt_pk_bf16_f32 v29, v29, v29
	v_bitop3_b32 v192, v45, s35, -16 bitop3:0x6c
	v_add3_u32 v209, v35, v192, v27
	ds_write_b16 v209, v29 offset:57600
	v_fma_f32 v29, v190, v18, v215
	v_cvt_pk_bf16_f32 v29, v29, v29
	v_bitop3_b32 v190, v45, s36, -16 bitop3:0x6c
	v_add3_u32 v210, v35, v190, v27
	ds_write_b16 v210, v29 offset:57856
	v_fma_f32 v29, v189, v18, v215
	v_cvt_pk_bf16_f32 v29, v29, v29
	v_bitop3_b32 v189, v45, s37, -16 bitop3:0x6c
	v_add3_u32 v211, v35, v189, v27
	ds_write_b16 v211, v29 offset:58112
	v_fma_f32 v29, v188, v18, v215
	v_cvt_pk_bf16_f32 v29, v29, v29
	v_bitop3_b32 v188, v45, s16, -16 bitop3:0x6c
	v_add3_u32 v212, v35, v188, v27
	ds_write_b16 v212, v29 offset:58368
	v_fma_f32 v29, v187, v18, v215
	v_cvt_pk_bf16_f32 v29, v29, v29
	v_bitop3_b32 v187, v45, s42, -16 bitop3:0x6c
	v_add3_u32 v213, v35, v187, v27
	ds_write_b16 v213, v29 offset:58624
	v_fma_f32 v29, v184, v18, v215
	v_cvt_pk_bf16_f32 v29, v29, v29
	v_bitop3_b32 v184, v45, s43, -16 bitop3:0x6c
	v_add3_u32 v214, v35, v184, v27
	ds_write_b16 v214, v29 offset:58880
	v_sub_f32_e32 v29, v182, v39
	v_mul_f32_e32 v29, v29, v18
	v_bfe_u32 v182, v29, 16, 1
	v_bitop3_b32 v45, v45, s94, -16 bitop3:0x6c
	v_add_u32_e32 v38, 0xd800, v35
	v_add3_u32 v29, v29, v182, s15
	v_add3_u32 v35, v35, v45, v27
	ds_write_b16_d16_hi v35, v29 offset:59136
	v_fma_f32 v29, v186, v18, v215
	v_cvt_pk_bf16_f32 v29, v29, v29
	ds_write_b16 v200, v29 offset:59392
	v_fma_f32 v29, v185, v18, v215
	v_cvt_pk_bf16_f32 v29, v29, v29
	ds_write_b16 v201, v29 offset:59648
	v_fma_f32 v29, v183, v18, v215
	v_cvt_pk_bf16_f32 v29, v29, v29
	ds_write_b16 v202, v29 offset:59904
	v_fma_f32 v29, v179, v18, v215
	v_cvt_pk_bf16_f32 v29, v29, v29
	ds_write_b16 v203, v29 offset:60160
	v_fma_f32 v29, v177, v18, v215
	v_cvt_pk_bf16_f32 v29, v29, v29
	ds_write_b16 v204, v29 offset:60416
	v_fma_f32 v29, v175, v18, v215
	v_cvt_pk_bf16_f32 v29, v29, v29
	ds_write_b16 v205, v29 offset:60672
	v_fma_f32 v29, v173, v18, v215
	v_cvt_pk_bf16_f32 v29, v29, v29
	ds_write_b16 v206, v29 offset:60928
	v_fma_f32 v29, v171, v18, v215
	v_cvt_pk_bf16_f32 v29, v29, v29
	ds_write_b16 v207, v29 offset:61184
	v_fma_f32 v29, v178, v18, v215
	v_cvt_pk_bf16_f32 v29, v29, v29
	ds_write_b16 v208, v29 offset:61440
	v_fma_f32 v29, v176, v18, v215
	v_cvt_pk_bf16_f32 v29, v29, v29
	ds_write_b16 v209, v29 offset:61696
	v_fma_f32 v29, v174, v18, v215
	v_cvt_pk_bf16_f32 v29, v29, v29
	ds_write_b16 v210, v29 offset:61952
	v_fma_f32 v29, v172, v18, v215
	v_cvt_pk_bf16_f32 v29, v29, v29
	ds_write_b16 v211, v29 offset:62208
	v_fma_f32 v29, v167, v18, v215
	v_cvt_pk_bf16_f32 v29, v29, v29
	ds_write_b16 v212, v29 offset:62464
	v_fma_f32 v29, v165, v18, v215
	v_cvt_pk_bf16_f32 v29, v29, v29
	ds_write_b16 v213, v29 offset:62720
	v_fma_f32 v29, v64, v18, v215
	v_cvt_pk_bf16_f32 v29, v29, v29
	ds_write_b16 v214, v29 offset:62976
	v_fma_f32 v29, v62, v18, v215
	v_cvt_pk_bf16_f32 v29, v29, v29
	ds_write_b16 v35, v29 offset:63232
	v_fma_f32 v29, v170, v18, v215
	v_cvt_pk_bf16_f32 v29, v29, v29
	ds_write_b16 v200, v29 offset:63488
	v_fma_f32 v29, v166, v18, v215
	v_cvt_pk_bf16_f32 v29, v29, v29
	ds_write_b16 v201, v29 offset:63744
	v_fma_f32 v29, v65, v18, v215
	v_cvt_pk_bf16_f32 v29, v29, v29
	ds_write_b16 v202, v29 offset:64000
	v_fma_f32 v29, v63, v18, v215
	v_cvt_pk_bf16_f32 v29, v29, v29
	ds_write_b16 v203, v29 offset:64256
	v_fma_f32 v29, v60, v18, v215
	v_cvt_pk_bf16_f32 v29, v29, v29
	ds_write_b16 v204, v29 offset:64512
	v_fma_f32 v29, v59, v18, v215
	v_cvt_pk_bf16_f32 v29, v29, v29
	ds_write_b16 v205, v29 offset:64768
	v_fma_f32 v29, v57, v18, v215
	v_cvt_pk_bf16_f32 v29, v29, v29
	ds_write_b16 v206, v29 offset:65024
	v_fma_f32 v29, v55, v18, v215
	v_cvt_pk_bf16_f32 v29, v29, v29
	ds_write_b16 v207, v29 offset:65280
	v_fma_f32 v29, v61, v18, v215
	v_cvt_pk_bf16_f32 v29, v29, v29
	v_add3_u32 v35, v38, v194, v27
	ds_write_b16 v35, v29 offset:10240
	v_fma_f32 v29, v58, v18, v215
	v_cvt_pk_bf16_f32 v29, v29, v29
	v_add3_u32 v55, v38, v192, v27
	ds_write_b16 v55, v29 offset:10496
	v_fma_f32 v29, v56, v18, v215
	v_cvt_pk_bf16_f32 v29, v29, v29
	v_add3_u32 v56, v38, v190, v27
	ds_write_b16 v56, v29 offset:10752
	v_fma_f32 v29, v54, v18, v215
	v_cvt_pk_bf16_f32 v29, v29, v29
	v_add3_u32 v54, v38, v189, v27
	ds_write_b16 v54, v29 offset:11008
	v_fma_f32 v29, v53, v18, v215
	v_cvt_pk_bf16_f32 v29, v29, v29
	v_add3_u32 v53, v38, v188, v27
	ds_write_b16 v53, v29 offset:11264
	v_fma_f32 v29, v51, v18, v215
	v_cvt_pk_bf16_f32 v29, v29, v29
	v_add3_u32 v51, v38, v187, v27
	ds_write_b16 v51, v29 offset:11520
	v_fma_f32 v29, v49, v18, v215
	v_cvt_pk_bf16_f32 v29, v29, v29
	v_add3_u32 v49, v38, v184, v27
	ds_write_b16 v49, v29 offset:11776
	v_fma_f32 v29, v47, v18, v215
	v_cvt_pk_bf16_f32 v29, v29, v29
	v_add3_u32 v45, v38, v45, v27
	ds_write_b16 v45, v29 offset:12032
	v_fma_f32 v29, v52, v18, v215
	v_cvt_pk_bf16_f32 v29, v29, v29
	v_add3_u32 v46, v38, v46, v27
	ds_write_b16 v46, v29 offset:12288
	v_fma_f32 v29, v50, v18, v215
	v_cvt_pk_bf16_f32 v29, v29, v29
	v_add3_u32 v46, v38, v199, v27
	ds_write_b16 v46, v29 offset:12544
	v_fma_f32 v29, v48, v18, v215
	v_cvt_pk_bf16_f32 v29, v29, v29
	v_add3_u32 v46, v38, v198, v27
	ds_write_b16 v46, v29 offset:12800
	v_mul_f32_e32 v29, v37, v18
	v_bfe_u32 v36, v29, 16, 1
	v_add3_u32 v29, v29, v36, s15
	v_add3_u32 v36, v38, v197, v27
	ds_write_b16_d16_hi v36, v29 offset:13056
	v_fma_f32 v29, v34, v18, v215
	v_cvt_pk_bf16_f32 v29, v29, v29
	v_add3_u32 v34, v38, v196, v27
	ds_write_b16 v34, v29 offset:13312
	v_sub_f32_e32 v29, v24, v39
	v_pk_fma_f32 v[24:25], v[40:41], s[22:23], v[24:25] op_sel_hi:[1,0,1] neg_lo:[1,0,0] neg_hi:[1,0,0]
	v_mul_f32_e32 v29, v29, v18
	v_mul_f32_e32 v24, v25, v18
	v_bfe_u32 v34, v29, 16, 1
	v_bfe_u32 v25, v24, 16, 1
	v_add3_u32 v29, v29, v34, s15
	v_add3_u32 v34, v38, v195, v27
	v_add3_u32 v24, v24, v25, s15
	v_add3_u32 v25, v38, v193, v27
	ds_write_b16_d16_hi v34, v29 offset:13568
	ds_write_b16_d16_hi v25, v24 offset:13824
	v_pk_fma_f32 v[24:25], v[40:41], s[22:23], v[32:33] op_sel_hi:[1,0,1] neg_lo:[1,0,0] neg_hi:[1,0,0]
	v_and_b32_e32 v167, 15, v43
	v_lshrrev_b32_e32 v216, 7, v43
	v_lshlrev_b32_e32 v216, 1, v216
	v_xor_b32_e32 v167, v216, v167
	v_mul_f32_e32 v24, v25, v18
	v_bfe_u32 v25, v24, 16, 1
	v_add3_u32 v24, v24, v25, s15
	v_add3_u32 v25, v38, v191, v27
	ds_write_b16_d16_hi v25, v24 offset:14080
	v_fma_f32 v24, v28, v18, v215
	v_cvt_pk_bf16_f32 v24, v24, v24
	ds_write_b16 v35, v24 offset:14336
	v_sub_f32_e32 v24, v22, v39
	v_pk_fma_f32 v[22:23], v[40:41], s[22:23], v[22:23] op_sel_hi:[1,0,1] neg_lo:[1,0,0] neg_hi:[1,0,0]
	v_mul_f32_e32 v24, v24, v18
	v_mul_f32_e32 v22, v23, v18
	v_bfe_u32 v25, v24, 16, 1
	v_bfe_u32 v23, v22, 16, 1
	v_add3_u32 v24, v24, v25, s15
	v_add3_u32 v22, v22, v23, s15
	ds_write_b16_d16_hi v55, v24 offset:14592
	ds_write_b16_d16_hi v56, v22 offset:14848
	v_pk_fma_f32 v[22:23], v[40:41], s[22:23], v[30:31] op_sel_hi:[1,0,1] neg_lo:[1,0,0] neg_hi:[1,0,0]
	s_nop 0
	v_mul_f32_e32 v22, v23, v18
	v_bfe_u32 v23, v22, 16, 1
	v_add3_u32 v22, v22, v23, s15
	ds_write_b16_d16_hi v54, v22 offset:15104
	v_fma_f32 v22, v26, v18, v215
	v_cvt_pk_bf16_f32 v22, v22, v22
	ds_write_b16 v53, v22 offset:15360
	v_sub_f32_e32 v22, v20, v39
	v_pk_fma_f32 v[20:21], v[40:41], s[22:23], v[20:21] op_sel_hi:[1,0,1] neg_lo:[1,0,0] neg_hi:[1,0,0]
	v_mul_f32_e32 v22, v22, v18
	v_mul_f32_e32 v20, v21, v18
	v_mul_f32_e32 v18, v19, v18
	v_bfe_u32 v23, v22, 16, 1
	v_bfe_u32 v21, v20, 16, 1
	v_bfe_u32 v19, v18, 16, 1
	v_add3_u32 v22, v22, v23, s15
	v_add3_u32 v20, v20, v21, s15
	v_add3_u32 v18, v18, v19, s15
	ds_write_b16_d16_hi v51, v22 offset:15616
	ds_write_b16_d16_hi v49, v20 offset:15872
	ds_write_b16_d16_hi v45, v18 offset:16128
	v_lshrrev_b32_e32 v18, 1, v43
	v_and_b32_e32 v18, 32, v18
	v_lshl_or_b32 v166, v44, 6, v18
	v_or_b32_e32 v18, v166, v168
	v_lshl_add_u32 v165, v18, 8, 32
	v_bitop3_b32 v18, v42, v167, 1 bitop3:0x6c
	v_lshl_add_u32 v18, v18, 4, v165
	v_and_b32_e32 v215, 31, v0
	v_add_u32_e32 v215, s3, v215
	v_lshlrev_b32_e32 v215, 12, v215
	v_and_b32_e32 v245, 0x1c0, v0
	v_add_u32_e32 v215, v215, v245
	v_bfe_u32 v245, v0, 5, 1
	v_lshl_add_u32 v245, v245, 3, v215
	v_bfe_u32 v215, v0, 5, 1
	v_lshl_add_u32 v215, v215, 3, v245
	global_load_dwordx4 v[216:219], v215, s[60:61] offset:3072
	global_load_dwordx4 v[220:223], v215, s[60:61] offset:3104
	s_add_u32 s98, s60, 0x20000
	s_addc_u32 s99, s61, 0
	global_load_dwordx4 v[224:227], v215, s[98:99] offset:3072
	global_load_dwordx4 v[228:231], v215, s[98:99] offset:3104
	s_add_u32 s100, s60, 0x40000
	s_addc_u32 s101, s61, 0
	global_load_dwordx4 v[232:235], v215, s[100:101] offset:3072
	global_load_dwordx4 v[236:239], v215, s[100:101] offset:3104
	s_add_u32 s98, s60, 0x60000
	s_addc_u32 s99, s61, 0
	global_load_dwordx4 v[252:255], v215, s[98:99] offset:3072
	global_load_dwordx2 v[240:241], v245, s[98:99] offset:3104
	global_load_dwordx2 v[246:247], v245, s[98:99] offset:3120
	s_waitcnt lgkmcnt(0)
	s_barrier
	ds_read_b128 v[170:173], v18 offset:55296
	s_waitcnt lgkmcnt(0)
	v_mfma_f32_32x32x16_bf16 v[50:65], v[170:173], v[2:5], 0
	v_mfma_f32_32x32x16_bf16 v[34:49], v[170:173], v[6:9], 0
	v_mfma_f32_32x32x16_bf16 v[18:33], v[170:173], v[10:13], 0
	v_mfma_f32_32x32x16_bf16 v[2:17], v[170:173], v[14:17], 0
	v_bitop3_b32 v170, v169, v167, 2 bitop3:0x36
	v_lshl_add_u32 v170, v170, 4, v165
	ds_read_b128 v[170:173], v170 offset:55296
	s_waitcnt lgkmcnt(0)
	v_mfma_f32_32x32x16_bf16 v[50:65], v[170:173], v[138:141], v[50:65]
	v_bitop3_b32 v138, v169, v167, 4 bitop3:0x36
	v_lshl_add_u32 v138, v138, 4, v165
	ds_read_b128 v[138:141], v138 offset:55296
	v_mfma_f32_32x32x16_bf16 v[34:49], v[170:173], v[142:145], v[34:49]
	v_mfma_f32_32x32x16_bf16 v[18:33], v[170:173], v[146:149], v[18:33]
	s_waitcnt lgkmcnt(0)
	v_mfma_f32_32x32x16_bf16 v[34:49], v[138:141], v[126:129], v[34:49]
	v_bitop3_b32 v126, v169, v167, 6 bitop3:0x36
	v_lshl_add_u32 v126, v126, 4, v165
	ds_read_b128 v[126:129], v126 offset:55296
	v_mfma_f32_32x32x16_bf16 v[2:17], v[170:173], v[150:153], v[2:17]
	v_mfma_f32_32x32x16_bf16 v[18:33], v[138:141], v[130:133], v[18:33]
	s_waitcnt lgkmcnt(0)
	v_mfma_f32_32x32x16_bf16 v[34:49], v[126:129], v[114:117], v[34:49]
	v_bitop3_b32 v114, v169, v167, 8 bitop3:0x36
	v_lshl_add_u32 v114, v114, 4, v165
	ds_read_b128 v[114:117], v114 offset:55296
	v_mfma_f32_32x32x16_bf16 v[2:17], v[138:141], v[134:137], v[2:17]
	v_mfma_f32_32x32x16_bf16 v[18:33], v[126:129], v[118:121], v[18:33]
	v_mfma_f32_32x32x16_bf16 v[2:17], v[126:129], v[122:125], v[2:17]
	v_lshlrev_b32_e32 v128, 7, v164
	v_or_b32_e32 v126, v128, v168
	v_ashrrev_i32_e32 v127, 31, v126
	v_lshlrev_b64 v[130:131], 2, v[126:127]
	v_lshl_or_b32 v122, v169, 2, v166
	v_or_b32_e32 v124, s3, v168
	v_mov_b32_e32 v125, s5
	s_waitcnt lgkmcnt(0)
	v_mfma_f32_32x32x16_bf16 v[18:33], v[114:117], v[106:109], v[18:33]
	v_bitop3_b32 v106, v169, v167, 10 bitop3:0x36
	v_lshl_add_u32 v106, v106, 4, v165
	ds_read_b128 v[106:109], v106 offset:55296
	v_lshl_add_u64 v[132:133], s[6:7], 0, v[130:131]
	v_lshl_add_u64 v[130:131], s[92:93], 0, v[130:131]
	v_ashrrev_i32_e32 v123, 31, v122
	v_lshlrev_b64 v[122:123], 1, v[122:123]
	v_mfma_f32_32x32x16_bf16 v[2:17], v[114:117], v[110:113], v[2:17]
	s_add_i32 s3, s3, s18
	s_cmpk_gt_i32 s4, 0x7f
	s_waitcnt lgkmcnt(0)
	v_mfma_f32_32x32x16_bf16 v[18:33], v[106:109], v[98:101], v[18:33]
	v_bitop3_b32 v98, v169, v167, 12 bitop3:0x36
	v_lshl_add_u32 v98, v98, 4, v165
	ds_read_b128 v[98:101], v98 offset:55296
	v_mfma_f32_32x32x16_bf16 v[2:17], v[106:109], v[102:105], v[2:17]
	s_waitcnt lgkmcnt(0)
	v_mfma_f32_32x32x16_bf16 v[2:17], v[98:101], v[94:97], v[2:17]
	v_bitop3_b32 v94, v169, v167, 14 bitop3:0x36
	v_lshl_add_u32 v94, v94, 4, v165
	ds_read_b128 v[94:97], v94 offset:55296
	v_ashrrev_i32_e32 v167, 31, v166
	s_waitcnt lgkmcnt(0)
	v_mfma_f32_32x32x16_bf16 v[2:17], v[94:97], v[90:93], v[2:17]
	v_lshlrev_b64 v[90:91], 2, v[166:167]
	v_lshl_add_u64 v[92:93], s[10:11], 0, v[90:91]
	v_lshl_add_u64 v[90:91], s[40:41], 0, v[90:91]
	v_lshl_add_u64 v[92:93], v[92:93], 0, v[154:155]
	v_lshl_add_u64 v[94:95], v[90:91], 0, v[154:155]
	global_load_dwordx4 v[114:117], v[92:93], off
	global_load_dwordx4 v[118:121], v[94:95], off
	global_load_dwordx4 v[106:109], v[92:93], off offset:32
	global_load_dwordx4 v[110:113], v[94:95], off offset:32
	global_load_dwordx4 v[98:101], v[92:93], off offset:64
	global_load_dwordx4 v[102:105], v[94:95], off offset:64
	s_nop 0
	global_load_dwordx4 v[90:93], v[92:93], off offset:96
	s_nop 0
	global_load_dwordx4 v[94:97], v[94:95], off offset:96
	s_nop 0
	global_load_dword v142, v[132:133], off
	global_load_dword v143, v[132:133], off offset:128
	global_load_dword v144, v[132:133], off offset:256
	global_load_dword v145, v[132:133], off offset:384
	global_load_dword v146, v[130:131], off
	global_load_dword v147, v[130:131], off offset:128
	global_load_dword v148, v[130:131], off offset:256
	global_load_dword v149, v[130:131], off offset:384
	v_lshlrev_b64 v[134:135], 11, v[124:125]
	v_lshl_add_u64 v[134:135], s[62:63], 0, v[134:135]
	v_lshl_add_u64 v[134:135], v[134:135], 0, v[122:123]
	v_add_co_u32_e32 v136, vcc, 0x10000, v134
	s_nop 1
	v_addc_co_u32_e32 v137, vcc, 0, v135, vcc
	v_add_co_u32_e32 v138, vcc, 0x20000, v134
	s_nop 1
	v_addc_co_u32_e32 v139, vcc, 0, v135, vcc
	v_add_co_u32_e32 v140, vcc, 0x30000, v134
	s_nop 1
	v_addc_co_u32_e32 v141, vcc, 0, v135, vcc
	v_and_b32_e32 v150, 31, v0
	v_lshlrev_b32_e32 v170, 6, v150
	v_bfe_u32 v151, v0, 5, 1
	v_lshl_add_u32 v170, v151, 3, v170
	v_lshrrev_b32_e32 v168, 6, v0
	v_lshl_add_u32 v170, v168, 13, v170
	v_add_u32_e32 v170, 0xd820, v170
	v_bfe_u32 v150, v0, 1, 2
	v_xor_b32_e32 v151, 0, v150
	v_lshl_add_u32 v152, v151, 4, v170
	v_xor_b32_e32 v151, 1, v150
	v_lshl_add_u32 v153, v151, 4, v170
	v_xor_b32_e32 v151, 2, v150
	v_lshl_add_u32 v164, v151, 4, v170
	v_xor_b32_e32 v151, 3, v150
	v_lshl_add_u32 v165, v151, 4, v170
	v_bfe_u32 v169, v0, 2, 4
	v_lshlrev_b32_e32 v166, 6, v169
	v_and_b32_e32 v151, 3, v0
	v_bfe_u32 v150, v0, 3, 2
	v_xor_b32_e32 v150, v151, v150
	v_lshl_add_u32 v166, v150, 4, v166
	v_lshl_add_u32 v166, v168, 13, v166
	v_add_u32_e32 v166, 0xd820, v166
	v_and_b32_e32 v167, -32, v124
	v_add_u32_e32 v167, v167, v169
	v_lshlrev_b32_e32 v167, 11, v167
	v_lshl_add_u32 v167, v168, 6, v167
	v_lshl_add_u32 v167, v151, 4, v167
	s_waitcnt vmcnt(0)
	s_nop 1
	v_permlane32_swap_b32 v216, v218
	v_permlane32_swap_b32 v217, v219
	v_permlane32_swap_b32 v220, v222
	v_permlane32_swap_b32 v221, v223
	v_permlane32_swap_b32 v224, v226
	v_permlane32_swap_b32 v225, v227
	v_permlane32_swap_b32 v228, v230
	v_permlane32_swap_b32 v229, v231
	v_permlane32_swap_b32 v232, v234
	v_permlane32_swap_b32 v233, v235
	v_permlane32_swap_b32 v236, v238
	v_permlane32_swap_b32 v237, v239
	v_permlane32_swap_b32 v252, v254
	v_permlane32_swap_b32 v253, v255
	v_mul_f32_e32 v150, v118, v142
	v_fmac_f32_e32 v150, v50, v114
	v_add_f32_e32 v50, v146, v150
	v_lshlrev_b32_e32 v151, 16, v216
	v_mul_f32_e32 v50, v50, v151
	v_mul_f32_e32 v150, v119, v142
	v_fmac_f32_e32 v150, v51, v115
	v_add_f32_e32 v51, v146, v150
	v_and_b32_e32 v151, 0xffff0000, v216
	v_mul_f32_e32 v51, v51, v151
	v_mul_f32_e32 v150, v120, v142
	v_fmac_f32_e32 v150, v52, v116
	v_add_f32_e32 v52, v146, v150
	v_lshlrev_b32_e32 v151, 16, v217
	v_mul_f32_e32 v52, v52, v151
	v_mul_f32_e32 v150, v121, v142
	v_fmac_f32_e32 v150, v53, v117
	v_add_f32_e32 v53, v146, v150
	v_and_b32_e32 v151, 0xffff0000, v217
	v_mul_f32_e32 v53, v53, v151
	v_cvt_pk_bf16_f32 v50, v50, v51
	v_cvt_pk_bf16_f32 v51, v52, v53
	ds_write_b64 v152, v[50:51] offset:0
	v_mul_f32_e32 v150, v110, v142
	v_fmac_f32_e32 v150, v54, v106
	v_add_f32_e32 v54, v146, v150
	v_lshlrev_b32_e32 v151, 16, v218
	v_mul_f32_e32 v54, v54, v151
	v_mul_f32_e32 v150, v111, v142
	v_fmac_f32_e32 v150, v55, v107
	v_add_f32_e32 v55, v146, v150
	v_and_b32_e32 v151, 0xffff0000, v218
	v_mul_f32_e32 v55, v55, v151
	v_mul_f32_e32 v150, v112, v142
	v_fmac_f32_e32 v150, v56, v108
	v_add_f32_e32 v56, v146, v150
	v_lshlrev_b32_e32 v151, 16, v219
	v_mul_f32_e32 v56, v56, v151
	v_mul_f32_e32 v150, v113, v142
	v_fmac_f32_e32 v150, v57, v109
	v_add_f32_e32 v57, v146, v150
	v_and_b32_e32 v151, 0xffff0000, v219
	v_mul_f32_e32 v57, v57, v151
	v_cvt_pk_bf16_f32 v54, v54, v55
	v_cvt_pk_bf16_f32 v55, v56, v57
	ds_write_b64 v153, v[54:55] offset:0
	v_mul_f32_e32 v150, v102, v142
	v_fmac_f32_e32 v150, v58, v98
	v_add_f32_e32 v58, v146, v150
	v_lshlrev_b32_e32 v151, 16, v220
	v_mul_f32_e32 v58, v58, v151
	v_mul_f32_e32 v150, v103, v142
	v_fmac_f32_e32 v150, v59, v99
	v_add_f32_e32 v59, v146, v150
	v_and_b32_e32 v151, 0xffff0000, v220
	v_mul_f32_e32 v59, v59, v151
	v_mul_f32_e32 v150, v104, v142
	v_fmac_f32_e32 v150, v60, v100
	v_add_f32_e32 v60, v146, v150
	v_lshlrev_b32_e32 v151, 16, v221
	v_mul_f32_e32 v60, v60, v151
	v_mul_f32_e32 v150, v105, v142
	v_fmac_f32_e32 v150, v61, v101
	v_add_f32_e32 v61, v146, v150
	v_and_b32_e32 v151, 0xffff0000, v221
	v_mul_f32_e32 v61, v61, v151
	v_cvt_pk_bf16_f32 v58, v58, v59
	v_cvt_pk_bf16_f32 v59, v60, v61
	ds_write_b64 v164, v[58:59] offset:0
	v_mul_f32_e32 v150, v94, v142
	v_fmac_f32_e32 v150, v62, v90
	v_add_f32_e32 v62, v146, v150
	v_lshlrev_b32_e32 v151, 16, v222
	v_mul_f32_e32 v62, v62, v151
	v_mul_f32_e32 v150, v95, v142
	v_fmac_f32_e32 v150, v63, v91
	v_add_f32_e32 v63, v146, v150
	v_and_b32_e32 v151, 0xffff0000, v222
	v_mul_f32_e32 v63, v63, v151
	v_mul_f32_e32 v150, v96, v142
	v_fmac_f32_e32 v150, v64, v92
	v_add_f32_e32 v64, v146, v150
	v_lshlrev_b32_e32 v151, 16, v223
	v_mul_f32_e32 v64, v64, v151
	v_mul_f32_e32 v150, v97, v142
	v_fmac_f32_e32 v150, v65, v93
	v_add_f32_e32 v65, v146, v150
	v_and_b32_e32 v151, 0xffff0000, v223
	v_mul_f32_e32 v65, v65, v151
	v_cvt_pk_bf16_f32 v62, v62, v63
	v_cvt_pk_bf16_f32 v63, v64, v65
	ds_write_b64 v165, v[62:63] offset:0
	v_mul_f32_e32 v150, v118, v143
	v_fmac_f32_e32 v150, v34, v114
	v_add_f32_e32 v34, v147, v150
	v_lshlrev_b32_e32 v151, 16, v224
	v_mul_f32_e32 v34, v34, v151
	v_mul_f32_e32 v150, v119, v143
	v_fmac_f32_e32 v150, v35, v115
	v_add_f32_e32 v35, v147, v150
	v_and_b32_e32 v151, 0xffff0000, v224
	v_mul_f32_e32 v35, v35, v151
	v_mul_f32_e32 v150, v120, v143
	v_fmac_f32_e32 v150, v36, v116
	v_add_f32_e32 v36, v147, v150
	v_lshlrev_b32_e32 v151, 16, v225
	v_mul_f32_e32 v36, v36, v151
	v_mul_f32_e32 v150, v121, v143
	v_fmac_f32_e32 v150, v37, v117
	v_add_f32_e32 v37, v147, v150
	v_and_b32_e32 v151, 0xffff0000, v225
	v_mul_f32_e32 v37, v37, v151
	v_cvt_pk_bf16_f32 v34, v34, v35
	v_cvt_pk_bf16_f32 v35, v36, v37
	ds_write_b64 v152, v[34:35] offset:2048
	v_mul_f32_e32 v150, v110, v143
	v_fmac_f32_e32 v150, v38, v106
	v_add_f32_e32 v38, v147, v150
	v_lshlrev_b32_e32 v151, 16, v226
	v_mul_f32_e32 v38, v38, v151
	v_mul_f32_e32 v150, v111, v143
	v_fmac_f32_e32 v150, v39, v107
	v_add_f32_e32 v39, v147, v150
	v_and_b32_e32 v151, 0xffff0000, v226
	v_mul_f32_e32 v39, v39, v151
	v_mul_f32_e32 v150, v112, v143
	v_fmac_f32_e32 v150, v40, v108
	v_add_f32_e32 v40, v147, v150
	v_lshlrev_b32_e32 v151, 16, v227
	v_mul_f32_e32 v40, v40, v151
	v_mul_f32_e32 v150, v113, v143
	v_fmac_f32_e32 v150, v41, v109
	v_add_f32_e32 v41, v147, v150
	v_and_b32_e32 v151, 0xffff0000, v227
	v_mul_f32_e32 v41, v41, v151
	v_cvt_pk_bf16_f32 v38, v38, v39
	v_cvt_pk_bf16_f32 v39, v40, v41
	ds_write_b64 v153, v[38:39] offset:2048
	v_mul_f32_e32 v150, v102, v143
	v_fmac_f32_e32 v150, v42, v98
	v_add_f32_e32 v42, v147, v150
	v_lshlrev_b32_e32 v151, 16, v228
	v_mul_f32_e32 v42, v42, v151
	v_mul_f32_e32 v150, v103, v143
	v_fmac_f32_e32 v150, v43, v99
	v_add_f32_e32 v43, v147, v150
	v_and_b32_e32 v151, 0xffff0000, v228
	v_mul_f32_e32 v43, v43, v151
	v_mul_f32_e32 v150, v104, v143
	v_fmac_f32_e32 v150, v44, v100
	v_add_f32_e32 v44, v147, v150
	v_lshlrev_b32_e32 v151, 16, v229
	v_mul_f32_e32 v44, v44, v151
	v_mul_f32_e32 v150, v105, v143
	v_fmac_f32_e32 v150, v45, v101
	v_add_f32_e32 v45, v147, v150
	v_and_b32_e32 v151, 0xffff0000, v229
	v_mul_f32_e32 v45, v45, v151
	v_cvt_pk_bf16_f32 v42, v42, v43
	v_cvt_pk_bf16_f32 v43, v44, v45
	ds_write_b64 v164, v[42:43] offset:2048
	v_mul_f32_e32 v150, v94, v143
	v_fmac_f32_e32 v150, v46, v90
	v_add_f32_e32 v46, v147, v150
	v_lshlrev_b32_e32 v151, 16, v230
	v_mul_f32_e32 v46, v46, v151
	v_mul_f32_e32 v150, v95, v143
	v_fmac_f32_e32 v150, v47, v91
	v_add_f32_e32 v47, v147, v150
	v_and_b32_e32 v151, 0xffff0000, v230
	v_mul_f32_e32 v47, v47, v151
	v_mul_f32_e32 v150, v96, v143
	v_fmac_f32_e32 v150, v48, v92
	v_add_f32_e32 v48, v147, v150
	v_lshlrev_b32_e32 v151, 16, v231
	v_mul_f32_e32 v48, v48, v151
	v_mul_f32_e32 v150, v97, v143
	v_fmac_f32_e32 v150, v49, v93
	v_add_f32_e32 v49, v147, v150
	v_and_b32_e32 v151, 0xffff0000, v231
	v_mul_f32_e32 v49, v49, v151
	v_cvt_pk_bf16_f32 v46, v46, v47
	v_cvt_pk_bf16_f32 v47, v48, v49
	ds_write_b64 v165, v[46:47] offset:2048
	v_mul_f32_e32 v150, v118, v144
	v_fmac_f32_e32 v150, v18, v114
	v_add_f32_e32 v18, v148, v150
	v_lshlrev_b32_e32 v151, 16, v232
	v_mul_f32_e32 v18, v18, v151
	v_mul_f32_e32 v150, v119, v144
	v_fmac_f32_e32 v150, v19, v115
	v_add_f32_e32 v19, v148, v150
	v_and_b32_e32 v151, 0xffff0000, v232
	v_mul_f32_e32 v19, v19, v151
	v_mul_f32_e32 v150, v120, v144
	v_fmac_f32_e32 v150, v20, v116
	v_add_f32_e32 v20, v148, v150
	v_lshlrev_b32_e32 v151, 16, v233
	v_mul_f32_e32 v20, v20, v151
	v_mul_f32_e32 v150, v121, v144
	v_fmac_f32_e32 v150, v21, v117
	v_add_f32_e32 v21, v148, v150
	v_and_b32_e32 v151, 0xffff0000, v233
	v_mul_f32_e32 v21, v21, v151
	v_cvt_pk_bf16_f32 v18, v18, v19
	v_cvt_pk_bf16_f32 v19, v20, v21
	ds_write_b64 v152, v[18:19] offset:4096
	v_mul_f32_e32 v150, v110, v144
	v_fmac_f32_e32 v150, v22, v106
	v_add_f32_e32 v22, v148, v150
	v_lshlrev_b32_e32 v151, 16, v234
	v_mul_f32_e32 v22, v22, v151
	v_mul_f32_e32 v150, v111, v144
	v_fmac_f32_e32 v150, v23, v107
	v_add_f32_e32 v23, v148, v150
	v_and_b32_e32 v151, 0xffff0000, v234
	v_mul_f32_e32 v23, v23, v151
	v_mul_f32_e32 v150, v112, v144
	v_fmac_f32_e32 v150, v24, v108
	v_add_f32_e32 v24, v148, v150
	v_lshlrev_b32_e32 v151, 16, v235
	v_mul_f32_e32 v24, v24, v151
	v_mul_f32_e32 v150, v113, v144
	v_fmac_f32_e32 v150, v25, v109
	v_add_f32_e32 v25, v148, v150
	v_and_b32_e32 v151, 0xffff0000, v235
	v_mul_f32_e32 v25, v25, v151
	v_cvt_pk_bf16_f32 v22, v22, v23
	v_cvt_pk_bf16_f32 v23, v24, v25
	ds_write_b64 v153, v[22:23] offset:4096
	v_mul_f32_e32 v150, v102, v144
	v_fmac_f32_e32 v150, v26, v98
	v_add_f32_e32 v26, v148, v150
	v_lshlrev_b32_e32 v151, 16, v236
	v_mul_f32_e32 v26, v26, v151
	v_mul_f32_e32 v150, v103, v144
	v_fmac_f32_e32 v150, v27, v99
	v_add_f32_e32 v27, v148, v150
	v_and_b32_e32 v151, 0xffff0000, v236
	v_mul_f32_e32 v27, v27, v151
	v_mul_f32_e32 v150, v104, v144
	v_fmac_f32_e32 v150, v28, v100
	v_add_f32_e32 v28, v148, v150
	v_lshlrev_b32_e32 v151, 16, v237
	v_mul_f32_e32 v28, v28, v151
	v_mul_f32_e32 v150, v105, v144
	v_fmac_f32_e32 v150, v29, v101
	v_add_f32_e32 v29, v148, v150
	v_and_b32_e32 v151, 0xffff0000, v237
	v_mul_f32_e32 v29, v29, v151
	v_cvt_pk_bf16_f32 v26, v26, v27
	v_cvt_pk_bf16_f32 v27, v28, v29
	ds_write_b64 v164, v[26:27] offset:4096
	v_mul_f32_e32 v150, v94, v144
	v_fmac_f32_e32 v150, v30, v90
	v_add_f32_e32 v30, v148, v150
	v_lshlrev_b32_e32 v151, 16, v238
	v_mul_f32_e32 v30, v30, v151
	v_mul_f32_e32 v150, v95, v144
	v_fmac_f32_e32 v150, v31, v91
	v_add_f32_e32 v31, v148, v150
	v_and_b32_e32 v151, 0xffff0000, v238
	v_mul_f32_e32 v31, v31, v151
	v_mul_f32_e32 v150, v96, v144
	v_fmac_f32_e32 v150, v32, v92
	v_add_f32_e32 v32, v148, v150
	v_lshlrev_b32_e32 v151, 16, v239
	v_mul_f32_e32 v32, v32, v151
	v_mul_f32_e32 v150, v97, v144
	v_fmac_f32_e32 v150, v33, v93
	v_add_f32_e32 v33, v148, v150
	v_and_b32_e32 v151, 0xffff0000, v239
	v_mul_f32_e32 v33, v33, v151
	v_cvt_pk_bf16_f32 v30, v30, v31
	v_cvt_pk_bf16_f32 v31, v32, v33
	ds_write_b64 v165, v[30:31] offset:4096
	v_mul_f32_e32 v150, v118, v145
	v_fmac_f32_e32 v150, v2, v114
	v_add_f32_e32 v2, v149, v150
	v_lshlrev_b32_e32 v151, 16, v252
	v_mul_f32_e32 v2, v2, v151
	v_mul_f32_e32 v150, v119, v145
	v_fmac_f32_e32 v150, v3, v115
	v_add_f32_e32 v3, v149, v150
	v_and_b32_e32 v151, 0xffff0000, v252
	v_mul_f32_e32 v3, v3, v151
	v_mul_f32_e32 v150, v120, v145
	v_fmac_f32_e32 v150, v4, v116
	v_add_f32_e32 v4, v149, v150
	v_lshlrev_b32_e32 v151, 16, v253
	v_mul_f32_e32 v4, v4, v151
	v_mul_f32_e32 v150, v121, v145
	v_fmac_f32_e32 v150, v5, v117
	v_add_f32_e32 v5, v149, v150
	v_and_b32_e32 v151, 0xffff0000, v253
	v_mul_f32_e32 v5, v5, v151
	v_cvt_pk_bf16_f32 v2, v2, v3
	v_cvt_pk_bf16_f32 v3, v4, v5
	ds_write_b64 v152, v[2:3] offset:6144
	v_mul_f32_e32 v150, v110, v145
	v_fmac_f32_e32 v150, v6, v106
	v_add_f32_e32 v6, v149, v150
	v_lshlrev_b32_e32 v151, 16, v254
	v_mul_f32_e32 v6, v6, v151
	v_mul_f32_e32 v150, v111, v145
	v_fmac_f32_e32 v150, v7, v107
	v_add_f32_e32 v7, v149, v150
	v_and_b32_e32 v151, 0xffff0000, v254
	v_mul_f32_e32 v7, v7, v151
	v_mul_f32_e32 v150, v112, v145
	v_fmac_f32_e32 v150, v8, v108
	v_add_f32_e32 v8, v149, v150
	v_lshlrev_b32_e32 v151, 16, v255
	v_mul_f32_e32 v8, v8, v151
	v_mul_f32_e32 v150, v113, v145
	v_fmac_f32_e32 v150, v9, v109
	v_add_f32_e32 v9, v149, v150
	v_and_b32_e32 v151, 0xffff0000, v255
	v_mul_f32_e32 v9, v9, v151
	v_cvt_pk_bf16_f32 v6, v6, v7
	v_cvt_pk_bf16_f32 v7, v8, v9
	ds_write_b64 v153, v[6:7] offset:6144
	v_mul_f32_e32 v150, v102, v145
	v_fmac_f32_e32 v150, v10, v98
	v_add_f32_e32 v10, v149, v150
	v_lshlrev_b32_e32 v151, 16, v240
	v_mul_f32_e32 v10, v10, v151
	v_mul_f32_e32 v150, v103, v145
	v_fmac_f32_e32 v150, v11, v99
	v_add_f32_e32 v11, v149, v150
	v_and_b32_e32 v151, 0xffff0000, v240
	v_mul_f32_e32 v11, v11, v151
	v_mul_f32_e32 v150, v104, v145
	v_fmac_f32_e32 v150, v12, v100
	v_add_f32_e32 v12, v149, v150
	v_lshlrev_b32_e32 v151, 16, v241
	v_mul_f32_e32 v12, v12, v151
	v_mul_f32_e32 v150, v105, v145
	v_fmac_f32_e32 v150, v13, v101
	v_add_f32_e32 v13, v149, v150
	v_and_b32_e32 v151, 0xffff0000, v241
	v_mul_f32_e32 v13, v13, v151
	v_cvt_pk_bf16_f32 v10, v10, v11
	v_cvt_pk_bf16_f32 v11, v12, v13
	ds_write_b64 v164, v[10:11] offset:6144
	v_mul_f32_e32 v150, v94, v145
	v_fmac_f32_e32 v150, v14, v90
	v_add_f32_e32 v14, v149, v150
	v_lshlrev_b32_e32 v151, 16, v246
	v_mul_f32_e32 v14, v14, v151
	v_mul_f32_e32 v150, v95, v145
	v_fmac_f32_e32 v150, v15, v91
	v_add_f32_e32 v15, v149, v150
	v_and_b32_e32 v151, 0xffff0000, v246
	v_mul_f32_e32 v15, v15, v151
	v_mul_f32_e32 v150, v96, v145
	v_fmac_f32_e32 v150, v16, v92
	v_add_f32_e32 v16, v149, v150
	v_lshlrev_b32_e32 v151, 16, v247
	v_mul_f32_e32 v16, v16, v151
	v_mul_f32_e32 v150, v97, v145
	v_fmac_f32_e32 v150, v17, v93
	v_add_f32_e32 v17, v149, v150
	v_and_b32_e32 v151, 0xffff0000, v247
	v_mul_f32_e32 v17, v17, v151
	v_cvt_pk_bf16_f32 v14, v14, v15
	v_cvt_pk_bf16_f32 v15, v16, v17
	ds_write_b64 v165, v[14:15] offset:6144
	s_waitcnt lgkmcnt(0)
	ds_read_b128 v[2:5], v166 offset:0
	ds_read_b128 v[6:9], v166 offset:1024
	ds_read_b128 v[10:13], v166 offset:2048
	ds_read_b128 v[14:17], v166 offset:3072
	ds_read_b128 v[18:21], v166 offset:4096
	ds_read_b128 v[22:25], v166 offset:5120
	ds_read_b128 v[26:29], v166 offset:6144
	ds_read_b128 v[30:33], v166 offset:7168
	s_waitcnt lgkmcnt(7)
	global_store_dwordx4 v167, v[2:5], s[62:63] offset:1536
	v_add_u32_e32 v151, 0x8000, v167
	s_waitcnt lgkmcnt(6)
	global_store_dwordx4 v151, v[6:9], s[62:63] offset:1536
	v_add_u32_e32 v150, 0x10000, v167
	s_waitcnt lgkmcnt(5)
	global_store_dwordx4 v150, v[10:13], s[62:63] offset:1536
	v_add_u32_e32 v151, 0x18000, v167
	s_waitcnt lgkmcnt(4)
	global_store_dwordx4 v151, v[14:17], s[62:63] offset:1536
	v_add_u32_e32 v150, 0x20000, v167
	s_waitcnt lgkmcnt(3)
	global_store_dwordx4 v150, v[18:21], s[62:63] offset:1536
	v_add_u32_e32 v151, 0x28000, v167
	s_waitcnt lgkmcnt(2)
	global_store_dwordx4 v151, v[22:25], s[62:63] offset:1536
	v_add_u32_e32 v150, 0x30000, v167
	s_waitcnt lgkmcnt(1)
	global_store_dwordx4 v150, v[26:29], s[62:63] offset:1536
	v_add_u32_e32 v151, 0x38000, v167
	s_waitcnt lgkmcnt(0)
	global_store_dwordx4 v151, v[30:33], s[62:63] offset:1536
	s_barrier
	s_cbranch_scc0 .LBB0_779

.LBB0_849:
	v_mov_b32_e32 v43, v0
	s_ashr_i32 s5, s3, 31
	v_ashrrev_i32_e32 v44, 7, v43
	s_waitcnt vmcnt(7)
	v_add_u32_e32 v130, s2, v44
	v_ashrrev_i32_e32 v131, 31, v130
	v_and_b32_e32 v134, 31, v43
	s_waitcnt vmcnt(0)
	v_lshlrev_b64 v[2:3], 15, v[130:131]
	v_bfe_u32 v135, v43, 5, 1
	v_lshl_add_u64 v[2:3], s[56:57], 0, v[2:3]
	v_and_b32_e32 v18, 63, v43
	v_lshlrev_b32_e32 v18, 4, v18
	v_lshlrev_b32_e32 v154, 4, v135
	v_add_u32_e32 v18, 0x1000, v18
	v_add_co_u32_e32 v18, vcc, v2, v18
	s_nop 1
	v_addc_co_u32_e32 v19, vcc, 0, v3, vcc
	v_add_co_u32_e32 v20, vcc, s14, v18
	v_ashrrev_i32_e32 v45, 2, v43
	s_nop 0
	v_addc_co_u32_e32 v21, vcc, 0, v19, vcc
	v_add_co_u32_e32 v22, vcc, s17, v18
	global_load_dwordx4 v[2:5], v[18:19], off offset:-4096
	global_load_dwordx4 v[6:9], v[20:21], off offset:-4096
	v_addc_co_u32_e32 v23, vcc, 0, v19, vcc
	v_add_co_u32_e32 v24, vcc, s30, v18
	global_load_dwordx4 v[10:13], v[22:23], off offset:-4096
	s_nop 0
	v_addc_co_u32_e32 v25, vcc, 0, v19, vcc
	global_load_dwordx4 v[14:17], v[24:25], off offset:-4096
	global_load_dwordx4 v[114:117], v[18:19], off offset:-3072
	global_load_dwordx4 v[118:121], v[20:21], off offset:-3072
	global_load_dwordx4 v[122:125], v[22:23], off offset:-3072
	global_load_dwordx4 v[126:129], v[24:25], off offset:-3072
	global_load_dwordx4 v[102:105], v[20:21], off offset:-2048
	global_load_dwordx4 v[106:109], v[22:23], off offset:-2048
	global_load_dwordx4 v[110:113], v[24:25], off offset:-2048
	global_load_dwordx4 v[90:93], v[20:21], off offset:-1024
	global_load_dwordx4 v[94:97], v[22:23], off offset:-1024
	global_load_dwordx4 v[98:101], v[24:25], off offset:-1024
	global_load_dwordx4 v[82:85], v[22:23], off
	global_load_dwordx4 v[86:89], v[24:25], off
	global_load_dwordx4 v[74:77], v[22:23], off offset:1024
	global_load_dwordx4 v[78:81], v[24:25], off offset:1024
	global_load_dwordx4 v[70:73], v[24:25], off offset:2048
	global_load_dwordx4 v[66:69], v[24:25], off offset:3072
	v_add_u32_e32 v18, s3, v45
	v_ashrrev_i32_e32 v19, 31, v18
	v_lshlrev_b32_e32 v20, 6, v43
	v_lshlrev_b64 v[18:19], 12, v[18:19]
	v_and_b32_e32 v46, 0xc0, v20
	v_lshl_add_u64 v[18:19], s[60:61], 0, v[18:19]
	v_lshlrev_b32_e32 v20, 1, v46
	v_mov_b32_e32 v21, v155
	v_lshl_add_u64 v[34:35], v[18:19], 0, v[20:21]
	global_load_dwordx4 v[18:21], v[34:35], off offset:3632
	global_load_dwordx4 v[22:25], v[34:35], off offset:3616
	global_load_dwordx4 v[26:29], v[34:35], off offset:3600
	global_load_dwordx4 v[30:33], v[34:35], off offset:3584
	global_load_dwordx4 v[36:39], v[34:35], off offset:3680
	global_load_dwordx4 v[176:179], v[34:35], off offset:3664
	global_load_dwordx4 v[48:51], v[34:35], off offset:3648
	global_load_dwordx4 v[182:185], v[34:35], off offset:3696
	v_lshrrev_b32_e32 v42, 5, v43
	s_add_i32 s4, s4, s46
	s_waitcnt vmcnt(7)
	v_lshlrev_b32_e32 v144, 16, v18
	s_waitcnt vmcnt(6)
	v_lshlrev_b32_e32 v150, 16, v22
	s_waitcnt vmcnt(5)
	v_lshlrev_b32_e32 v168, 16, v26
	s_waitcnt vmcnt(4)
	v_lshlrev_b32_e32 v174, 16, v30
	v_and_b32_e32 v173, 0xffff0000, v30
	v_add_f32_e32 v30, 0, v174
	v_lshlrev_b32_e32 v172, 16, v31
	v_add_f32_e32 v30, v30, v173
	v_and_b32_e32 v171, 0xffff0000, v31
	v_mul_f32_e32 v31, v173, v173
	v_add_f32_e32 v30, v30, v172
	v_lshlrev_b32_e32 v170, 16, v32
	v_fmac_f32_e32 v31, v174, v174
	v_add_f32_e32 v30, v30, v171
	v_and_b32_e32 v169, 0xffff0000, v32
	v_fmac_f32_e32 v31, v172, v172
	v_add_f32_e32 v30, v30, v170
	v_lshlrev_b32_e32 v167, 16, v33
	v_fmac_f32_e32 v31, v171, v171
	v_add_f32_e32 v30, v30, v169
	v_and_b32_e32 v165, 0xffff0000, v33
	v_fmac_f32_e32 v31, v170, v170
	v_add_f32_e32 v30, v30, v167
	v_fmac_f32_e32 v31, v169, v169
	v_add_f32_e32 v30, v30, v165
	v_fmac_f32_e32 v31, v167, v167
	v_and_b32_e32 v166, 0xffff0000, v26
	v_add_f32_e32 v26, v30, v168
	v_fmac_f32_e32 v31, v165, v165
	v_lshlrev_b32_e32 v164, 16, v27
	v_add_f32_e32 v26, v26, v166
	v_and_b32_e32 v153, 0xffff0000, v27
	v_fmac_f32_e32 v31, v168, v168
	v_add_f32_e32 v26, v26, v164
	v_lshlrev_b32_e32 v152, 16, v28
	v_fmac_f32_e32 v31, v166, v166
	v_add_f32_e32 v26, v26, v153
	v_and_b32_e32 v151, 0xffff0000, v28
	v_fmac_f32_e32 v31, v164, v164
	v_add_f32_e32 v26, v26, v152
	v_lshlrev_b32_e32 v148, 16, v29
	v_fmac_f32_e32 v31, v153, v153
	v_add_f32_e32 v26, v26, v151
	v_and_b32_e32 v146, 0xffff0000, v29
	v_fmac_f32_e32 v31, v152, v152
	v_add_f32_e32 v26, v26, v148
	v_fmac_f32_e32 v31, v151, v151
	v_add_f32_e32 v26, v26, v146
	v_fmac_f32_e32 v31, v148, v148
	v_and_b32_e32 v149, 0xffff0000, v22
	v_add_f32_e32 v22, v26, v150
	v_fmac_f32_e32 v31, v146, v146
	v_lshlrev_b32_e32 v147, 16, v23
	v_add_f32_e32 v22, v22, v149
	v_and_b32_e32 v145, 0xffff0000, v23
	v_fmac_f32_e32 v31, v150, v150
	v_add_f32_e32 v22, v22, v147
	v_lshlrev_b32_e32 v143, 16, v24
	v_fmac_f32_e32 v31, v149, v149
	v_add_f32_e32 v22, v22, v145
	v_and_b32_e32 v141, 0xffff0000, v24
	v_fmac_f32_e32 v31, v147, v147
	v_add_f32_e32 v22, v22, v143
	v_lshlrev_b32_e32 v139, 16, v25
	v_fmac_f32_e32 v31, v145, v145
	v_add_f32_e32 v22, v22, v141
	v_and_b32_e32 v137, 0xffff0000, v25
	v_fmac_f32_e32 v31, v143, v143
	v_add_f32_e32 v22, v22, v139
	v_fmac_f32_e32 v31, v141, v141
	v_add_f32_e32 v22, v22, v137
	v_fmac_f32_e32 v31, v139, v139
	v_and_b32_e32 v142, 0xffff0000, v18
	v_add_f32_e32 v18, v22, v144
	v_fmac_f32_e32 v31, v137, v137
	v_lshlrev_b32_e32 v140, 16, v19
	v_add_f32_e32 v18, v18, v142
	v_and_b32_e32 v138, 0xffff0000, v19
	v_fmac_f32_e32 v31, v144, v144
	v_add_f32_e32 v18, v18, v140
	v_lshlrev_b32_e32 v133, 16, v20
	v_fmac_f32_e32 v31, v142, v142
	v_add_f32_e32 v18, v18, v138
	v_and_b32_e32 v131, 0xffff0000, v20
	v_fmac_f32_e32 v31, v140, v140
	v_add_f32_e32 v18, v18, v133
	v_lshlrev_b32_e32 v64, 16, v21
	v_fmac_f32_e32 v31, v138, v138
	v_add_f32_e32 v18, v18, v131
	v_and_b32_e32 v62, 0xffff0000, v21
	v_fmac_f32_e32 v31, v133, v133
	v_add_f32_e32 v18, v18, v64
	v_fmac_f32_e32 v31, v131, v131
	v_add_f32_e32 v18, v18, v62
	s_waitcnt vmcnt(1)
	v_lshlrev_b32_e32 v136, 16, v48
	v_fmac_f32_e32 v31, v64, v64
	v_and_b32_e32 v132, 0xffff0000, v48
	v_add_f32_e32 v18, v18, v136
	v_fmac_f32_e32 v31, v62, v62
	v_lshlrev_b32_e32 v65, 16, v49
	v_add_f32_e32 v18, v18, v132
	v_and_b32_e32 v63, 0xffff0000, v49
	v_fmac_f32_e32 v31, v136, v136
	v_add_f32_e32 v18, v18, v65
	v_lshlrev_b32_e32 v60, 16, v50
	v_fmac_f32_e32 v31, v132, v132
	v_add_f32_e32 v18, v18, v63
	v_and_b32_e32 v59, 0xffff0000, v50
	v_fmac_f32_e32 v31, v65, v65
	v_add_f32_e32 v18, v18, v60
	v_lshlrev_b32_e32 v57, 16, v51
	v_fmac_f32_e32 v31, v63, v63
	v_add_f32_e32 v18, v18, v59
	v_and_b32_e32 v55, 0xffff0000, v51
	v_fmac_f32_e32 v31, v60, v60
	v_add_f32_e32 v18, v18, v57
	v_fmac_f32_e32 v31, v59, v59
	v_add_f32_e32 v18, v18, v55
	v_lshlrev_b32_e32 v61, 16, v176
	v_fmac_f32_e32 v31, v57, v57
	v_and_b32_e32 v58, 0xffff0000, v176
	v_add_f32_e32 v18, v18, v61
	v_fmac_f32_e32 v31, v55, v55
	v_lshlrev_b32_e32 v56, 16, v177
	v_add_f32_e32 v18, v18, v58
	v_and_b32_e32 v54, 0xffff0000, v177
	v_fmac_f32_e32 v31, v61, v61
	v_add_f32_e32 v18, v18, v56
	v_lshlrev_b32_e32 v53, 16, v178
	v_fmac_f32_e32 v31, v58, v58
	v_add_f32_e32 v18, v18, v54
	v_and_b32_e32 v51, 0xffff0000, v178
	v_fmac_f32_e32 v31, v56, v56
	v_add_f32_e32 v18, v18, v53
	v_lshlrev_b32_e32 v49, 16, v179
	v_fmac_f32_e32 v31, v54, v54
	v_add_f32_e32 v18, v18, v51
	v_and_b32_e32 v47, 0xffff0000, v179
	v_fmac_f32_e32 v31, v53, v53
	v_add_f32_e32 v18, v18, v49
	v_fmac_f32_e32 v31, v51, v51
	v_add_f32_e32 v18, v18, v47
	v_lshlrev_b32_e32 v52, 16, v36
	v_fmac_f32_e32 v31, v49, v49
	v_and_b32_e32 v50, 0xffff0000, v36
	v_add_f32_e32 v18, v18, v52
	v_fmac_f32_e32 v31, v47, v47
	v_lshlrev_b32_e32 v48, 16, v37
	v_add_f32_e32 v18, v18, v50
	v_fmac_f32_e32 v31, v52, v52
	v_add_f32_e32 v18, v18, v48
	v_and_b32_e32 v37, 0xffff0000, v37
	v_fmac_f32_e32 v31, v50, v50
	v_lshlrev_b32_e32 v34, 16, v38
	v_mov_b32_e32 v35, v37
	v_add_f32_e32 v20, v18, v37
	v_fmac_f32_e32 v31, v48, v48
	v_and_b32_e32 v24, 0xffff0000, v38
	v_pk_mul_f32 v[18:19], v[34:35], v[34:35]
	v_add_f32_e32 v20, v20, v34
	v_lshlrev_b32_e32 v25, 16, v39
	v_add_f32_e32 v19, v19, v31
	v_add_f32_e32 v20, v20, v24
	v_add_f32_e32 v21, v18, v19
	v_pk_mul_f32 v[18:19], v[24:25], v[24:25]
	v_add_f32_e32 v20, v20, v25
	v_and_b32_e32 v33, 0xffff0000, v39
	v_add_f32_e32 v18, v18, v21
	s_waitcnt vmcnt(0)
	v_lshlrev_b32_e32 v28, 16, v182
	v_mov_b32_e32 v29, v33
	v_add_f32_e32 v20, v20, v33
	v_add_f32_e32 v21, v19, v18
	v_and_b32_e32 v22, 0xffff0000, v182
	v_pk_mul_f32 v[18:19], v[28:29], v[28:29]
	v_add_f32_e32 v20, v20, v28
	v_lshlrev_b32_e32 v23, 16, v183
	v_add_f32_e32 v19, v19, v21
	v_add_f32_e32 v20, v20, v22
	v_add_f32_e32 v21, v18, v19
	v_pk_mul_f32 v[18:19], v[22:23], v[22:23]
	v_add_f32_e32 v29, v20, v23
	v_and_b32_e32 v31, 0xffff0000, v183
	v_add_f32_e32 v18, v18, v21
	v_lshlrev_b32_e32 v26, 16, v184
	v_mov_b32_e32 v27, v31
	v_add_f32_e32 v29, v29, v31
	v_and_b32_e32 v36, s0, v38
	v_add_f32_e32 v18, v19, v18
	v_and_b32_e32 v20, 0xffff0000, v184
	v_pk_mul_f32 v[38:39], v[26:27], v[26:27]
	v_add_f32_e32 v27, v29, v26
	v_lshlrev_b32_e32 v21, 16, v185
	v_add_f32_e32 v18, v39, v18
	v_add_f32_e32 v27, v27, v20
	v_and_b32_e32 v29, 64, v181
	v_add_f32_e32 v18, v38, v18
	v_pk_mul_f32 v[40:41], v[20:21], v[20:21]
	v_add_f32_e32 v39, v27, v21
	v_xor_b32_e32 v27, 1, v181
	v_add_u32_e32 v29, 64, v29
	v_and_b32_e32 v19, 0xffff0000, v185
	v_add_f32_e32 v18, v40, v18
	v_cmp_lt_i32_e32 vcc, v27, v29
	v_add_f32_e32 v18, v41, v18
	v_mul_f32_e32 v38, v19, v19
	v_cndmask_b32_e32 v27, v181, v27, vcc
	v_lshlrev_b32_e32 v27, 2, v27
	v_pk_add_f32 v[38:39], v[38:39], v[18:19]
	s_nop 1
	v_mov_b32_dpp v41, v39 quad_perm:[1,0,3,2] row_mask:0xf bank_mask:0xf
	v_mov_b32_dpp v40, v38 quad_perm:[1,0,3,2] row_mask:0xf bank_mask:0xf
	v_xor_b32_e32 v35, 2, v181
	v_cmp_lt_i32_e32 vcc, v35, v29
	v_and_b32_e32 v30, s0, v182
	v_mov_b32_e32 v32, v36
	v_cndmask_b32_e32 v29, v181, v35, vcc
	v_lshlrev_b32_e32 v29, 2, v29
	s_waitcnt lgkmcnt(0)
	v_pk_add_f32 v[38:39], v[38:39], v[40:41]
	s_nop 1
	v_mov_b32_dpp v41, v39 quad_perm:[2,3,0,1] row_mask:0xf bank_mask:0xf
	v_mov_b32_dpp v40, v38 quad_perm:[2,3,0,1] row_mask:0xf bank_mask:0xf
	s_waitcnt lgkmcnt(0)
	v_pk_add_f32 v[40:41], v[38:39], v[40:41]
	s_nop 0
	v_pk_mul_f32 v[38:39], v[40:41], s[22:23] op_sel_hi:[1,0]
	v_pk_fma_f32 v[36:37], v[40:41], s[22:23], v[36:37] op_sel_hi:[1,0,1] neg_lo:[1,0,0] neg_hi:[1,0,0]
	v_fma_f32 v18, -v39, v39, v38
	v_max_f32_e32 v18, 0, v18
	v_add_f32_e32 v18, 0x358637bd, v18
	v_cmp_gt_f32_e32 vcc, s33, v18
	v_mul_f32_e32 v27, 0x4b800000, v18
	v_sub_f32_e32 v29, v174, v39
	v_cndmask_b32_e32 v18, v18, v27, vcc
	v_rsq_f32_e32 v18, v18
	v_sub_f32_e32 v19, v19, v39
	v_mul_f32_e32 v27, 0x45800000, v18
	v_cndmask_b32_e32 v18, v18, v27, vcc
	v_mul_f32_e32 v29, v29, v18
	v_lshlrev_b32_e32 v27, 1, v45
	v_bfe_u32 v35, v29, 16, 1
	v_ashrrev_i32_e32 v45, 1, v43
	v_and_b32_e32 v216, 3, v43
	v_lshlrev_b32_e32 v216, 5, v216
	v_xor_b32_e32 v45, v216, v45
	v_and_b32_e32 v27, 14, v27
	v_add3_u32 v29, v29, v35, s15
	v_lshl_add_u32 v35, v46, 8, 32
	v_and_b32_e32 v46, -16, v45
	v_add3_u32 v174, v35, v46, v27
	ds_write_b16_d16_hi v174, v29 offset:55296
	v_mul_f32_e64 v215, -v39, v18
	v_fma_f32 v29, v173, v18, v215
	v_cvt_pk_bf16_f32 v29, v29, v29
	v_bitop3_b32 v173, v45, 16, -16 bitop3:0x6c
	v_add3_u32 v175, v35, v173, v27
	ds_write_b16 v175, v29 offset:55552
	v_fma_f32 v29, v172, v18, v215
	v_cvt_pk_bf16_f32 v29, v29, v29
	v_bitop3_b32 v172, v45, 32, -16 bitop3:0x6c
	v_add3_u32 v176, v35, v172, v27
	ds_write_b16 v176, v29 offset:55808
	v_fma_f32 v29, v171, v18, v215
	v_cvt_pk_bf16_f32 v29, v29, v29
	v_bitop3_b32 v171, v45, 48, -16 bitop3:0x6c
	v_add3_u32 v177, v35, v171, v27
	ds_write_b16 v177, v29 offset:56064
	v_fma_f32 v29, v170, v18, v215
	v_cvt_pk_bf16_f32 v29, v29, v29
	v_bitop3_b32 v170, v45, 64, -16 bitop3:0x6c
	v_add3_u32 v178, v35, v170, v27
	ds_write_b16 v178, v29 offset:56320
	v_fma_f32 v29, v169, v18, v215
	v_cvt_pk_bf16_f32 v29, v29, v29
	v_bitop3_b32 v169, v45, s34, -16 bitop3:0x6c
	v_add3_u32 v179, v35, v169, v27
	ds_write_b16 v179, v29 offset:56576
	v_fma_f32 v29, v167, v18, v215
	v_cvt_pk_bf16_f32 v29, v29, v29
	v_bitop3_b32 v167, v45, s31, -16 bitop3:0x6c
	v_add3_u32 v182, v35, v167, v27
	ds_write_b16 v182, v29 offset:56832
	v_fma_f32 v29, v165, v18, v215
	v_cvt_pk_bf16_f32 v29, v29, v29
	v_bitop3_b32 v165, v45, s13, -16 bitop3:0x6c
	v_add3_u32 v183, v35, v165, v27
	ds_write_b16 v183, v29 offset:57088
	v_fma_f32 v29, v168, v18, v215
	v_cvt_pk_bf16_f32 v29, v29, v29
	v_bitop3_b32 v168, v45, s12, -16 bitop3:0x6c
	v_add3_u32 v184, v35, v168, v27
	ds_write_b16 v184, v29 offset:57344
	v_fma_f32 v29, v166, v18, v215
	v_cvt_pk_bf16_f32 v29, v29, v29
	v_bitop3_b32 v166, v45, s35, -16 bitop3:0x6c
	v_add3_u32 v185, v35, v166, v27
	ds_write_b16 v185, v29 offset:57600
	v_fma_f32 v29, v164, v18, v215
	v_cvt_pk_bf16_f32 v29, v29, v29
	v_bitop3_b32 v164, v45, s38, -16 bitop3:0x6c
	v_add3_u32 v186, v35, v164, v27
	ds_write_b16 v186, v29 offset:57856
	v_fma_f32 v29, v153, v18, v215
	v_cvt_pk_bf16_f32 v29, v29, v29
	v_bitop3_b32 v153, v45, s39, -16 bitop3:0x6c
	v_add3_u32 v187, v35, v153, v27
	ds_write_b16 v187, v29 offset:58112
	v_fma_f32 v29, v152, v18, v215
	v_cvt_pk_bf16_f32 v29, v29, v29
	v_bitop3_b32 v152, v45, s16, -16 bitop3:0x6c
	v_add3_u32 v188, v35, v152, v27
	ds_write_b16 v188, v29 offset:58368
	v_fma_f32 v29, v151, v18, v215
	v_cvt_pk_bf16_f32 v29, v29, v29
	v_bitop3_b32 v151, v45, s40, -16 bitop3:0x6c
	v_add3_u32 v189, v35, v151, v27
	ds_write_b16 v189, v29 offset:58624
	v_fma_f32 v29, v148, v18, v215
	v_cvt_pk_bf16_f32 v29, v29, v29
	v_bitop3_b32 v148, v45, s41, -16 bitop3:0x6c
	v_add3_u32 v190, v35, v148, v27
	ds_write_b16 v190, v29 offset:58880
	v_sub_f32_e32 v29, v146, v39
	v_mul_f32_e32 v29, v29, v18
	v_bfe_u32 v146, v29, 16, 1
	v_bitop3_b32 v45, v45, s42, -16 bitop3:0x6c
	v_add_u32_e32 v38, 0xd800, v35
	v_add3_u32 v29, v29, v146, s15
	v_add3_u32 v35, v35, v45, v27
	ds_write_b16_d16_hi v35, v29 offset:59136
	v_fma_f32 v29, v150, v18, v215
	v_cvt_pk_bf16_f32 v29, v29, v29
	ds_write_b16 v174, v29 offset:59392
	v_fma_f32 v29, v149, v18, v215
	v_cvt_pk_bf16_f32 v29, v29, v29
	ds_write_b16 v175, v29 offset:59648
	v_fma_f32 v29, v147, v18, v215
	v_cvt_pk_bf16_f32 v29, v29, v29
	ds_write_b16 v176, v29 offset:59904
	v_fma_f32 v29, v145, v18, v215
	v_cvt_pk_bf16_f32 v29, v29, v29
	ds_write_b16 v177, v29 offset:60160
	v_fma_f32 v29, v143, v18, v215
	v_cvt_pk_bf16_f32 v29, v29, v29
	ds_write_b16 v178, v29 offset:60416
	v_fma_f32 v29, v141, v18, v215
	v_cvt_pk_bf16_f32 v29, v29, v29
	ds_write_b16 v179, v29 offset:60672
	v_fma_f32 v29, v139, v18, v215
	v_cvt_pk_bf16_f32 v29, v29, v29
	ds_write_b16 v182, v29 offset:60928
	v_fma_f32 v29, v137, v18, v215
	v_cvt_pk_bf16_f32 v29, v29, v29
	ds_write_b16 v183, v29 offset:61184
	v_fma_f32 v29, v144, v18, v215
	v_cvt_pk_bf16_f32 v29, v29, v29
	ds_write_b16 v184, v29 offset:61440
	v_fma_f32 v29, v142, v18, v215
	v_cvt_pk_bf16_f32 v29, v29, v29
	ds_write_b16 v185, v29 offset:61696
	v_fma_f32 v29, v140, v18, v215
	v_cvt_pk_bf16_f32 v29, v29, v29
	ds_write_b16 v186, v29 offset:61952
	v_fma_f32 v29, v138, v18, v215
	v_cvt_pk_bf16_f32 v29, v29, v29
	ds_write_b16 v187, v29 offset:62208
	v_fma_f32 v29, v133, v18, v215
	v_cvt_pk_bf16_f32 v29, v29, v29
	ds_write_b16 v188, v29 offset:62464
	v_fma_f32 v29, v131, v18, v215
	v_cvt_pk_bf16_f32 v29, v29, v29
	ds_write_b16 v189, v29 offset:62720
	v_fma_f32 v29, v64, v18, v215
	v_cvt_pk_bf16_f32 v29, v29, v29
	ds_write_b16 v190, v29 offset:62976
	v_fma_f32 v29, v62, v18, v215
	v_cvt_pk_bf16_f32 v29, v29, v29
	ds_write_b16 v35, v29 offset:63232
	v_fma_f32 v29, v136, v18, v215
	v_cvt_pk_bf16_f32 v29, v29, v29
	ds_write_b16 v174, v29 offset:63488
	v_fma_f32 v29, v132, v18, v215
	v_cvt_pk_bf16_f32 v29, v29, v29
	ds_write_b16 v175, v29 offset:63744
	v_fma_f32 v29, v65, v18, v215
	v_cvt_pk_bf16_f32 v29, v29, v29
	ds_write_b16 v176, v29 offset:64000
	v_fma_f32 v29, v63, v18, v215
	v_cvt_pk_bf16_f32 v29, v29, v29
	ds_write_b16 v177, v29 offset:64256
	v_fma_f32 v29, v60, v18, v215
	v_cvt_pk_bf16_f32 v29, v29, v29
	ds_write_b16 v178, v29 offset:64512
	v_fma_f32 v29, v59, v18, v215
	v_cvt_pk_bf16_f32 v29, v29, v29
	ds_write_b16 v179, v29 offset:64768
	v_fma_f32 v29, v57, v18, v215
	v_cvt_pk_bf16_f32 v29, v29, v29
	ds_write_b16 v182, v29 offset:65024
	v_fma_f32 v29, v55, v18, v215
	v_cvt_pk_bf16_f32 v29, v29, v29
	ds_write_b16 v183, v29 offset:65280
	v_fma_f32 v29, v61, v18, v215
	v_cvt_pk_bf16_f32 v29, v29, v29
	v_add3_u32 v35, v38, v168, v27
	ds_write_b16 v35, v29 offset:10240
	v_fma_f32 v29, v58, v18, v215
	v_cvt_pk_bf16_f32 v29, v29, v29
	v_add3_u32 v55, v38, v166, v27
	ds_write_b16 v55, v29 offset:10496
	v_fma_f32 v29, v56, v18, v215
	v_cvt_pk_bf16_f32 v29, v29, v29
	v_add3_u32 v56, v38, v164, v27
	ds_write_b16 v56, v29 offset:10752
	v_fma_f32 v29, v54, v18, v215
	v_cvt_pk_bf16_f32 v29, v29, v29
	v_add3_u32 v54, v38, v153, v27
	ds_write_b16 v54, v29 offset:11008
	v_fma_f32 v29, v53, v18, v215
	v_cvt_pk_bf16_f32 v29, v29, v29
	v_add3_u32 v53, v38, v152, v27
	ds_write_b16 v53, v29 offset:11264
	v_fma_f32 v29, v51, v18, v215
	v_cvt_pk_bf16_f32 v29, v29, v29
	v_add3_u32 v51, v38, v151, v27
	ds_write_b16 v51, v29 offset:11520
	v_fma_f32 v29, v49, v18, v215
	v_cvt_pk_bf16_f32 v29, v29, v29
	v_add3_u32 v49, v38, v148, v27
	ds_write_b16 v49, v29 offset:11776
	v_fma_f32 v29, v47, v18, v215
	v_cvt_pk_bf16_f32 v29, v29, v29
	v_add3_u32 v45, v38, v45, v27
	ds_write_b16 v45, v29 offset:12032
	v_fma_f32 v29, v52, v18, v215
	v_cvt_pk_bf16_f32 v29, v29, v29
	v_add3_u32 v46, v38, v46, v27
	ds_write_b16 v46, v29 offset:12288
	v_fma_f32 v29, v50, v18, v215
	v_cvt_pk_bf16_f32 v29, v29, v29
	v_add3_u32 v46, v38, v173, v27
	ds_write_b16 v46, v29 offset:12544
	v_fma_f32 v29, v48, v18, v215
	v_cvt_pk_bf16_f32 v29, v29, v29
	v_add3_u32 v46, v38, v172, v27
	ds_write_b16 v46, v29 offset:12800
	v_mul_f32_e32 v29, v37, v18
	v_bfe_u32 v36, v29, 16, 1
	v_add3_u32 v29, v29, v36, s15
	v_add3_u32 v36, v38, v171, v27
	ds_write_b16_d16_hi v36, v29 offset:13056
	v_fma_f32 v29, v34, v18, v215
	v_cvt_pk_bf16_f32 v29, v29, v29
	v_add3_u32 v34, v38, v170, v27
	ds_write_b16 v34, v29 offset:13312
	v_sub_f32_e32 v29, v24, v39
	v_pk_fma_f32 v[24:25], v[40:41], s[22:23], v[24:25] op_sel_hi:[1,0,1] neg_lo:[1,0,0] neg_hi:[1,0,0]
	v_mul_f32_e32 v29, v29, v18
	v_mul_f32_e32 v24, v25, v18
	v_bfe_u32 v34, v29, 16, 1
	v_bfe_u32 v25, v24, 16, 1
	v_add3_u32 v29, v29, v34, s15
	v_add3_u32 v34, v38, v169, v27
	v_add3_u32 v24, v24, v25, s15
	v_add3_u32 v25, v38, v167, v27
	ds_write_b16_d16_hi v34, v29 offset:13568
	ds_write_b16_d16_hi v25, v24 offset:13824
	v_pk_fma_f32 v[24:25], v[40:41], s[22:23], v[32:33] op_sel_hi:[1,0,1] neg_lo:[1,0,0] neg_hi:[1,0,0]
	v_and_b32_e32 v133, 15, v43
	v_lshrrev_b32_e32 v216, 7, v43
	v_lshlrev_b32_e32 v216, 1, v216
	v_xor_b32_e32 v133, v216, v133
	v_mul_f32_e32 v24, v25, v18
	v_bfe_u32 v25, v24, 16, 1
	v_add3_u32 v24, v24, v25, s15
	v_add3_u32 v25, v38, v165, v27
	ds_write_b16_d16_hi v25, v24 offset:14080
	v_fma_f32 v24, v28, v18, v215
	v_cvt_pk_bf16_f32 v24, v24, v24
	ds_write_b16 v35, v24 offset:14336
	v_sub_f32_e32 v24, v22, v39
	v_pk_fma_f32 v[22:23], v[40:41], s[22:23], v[22:23] op_sel_hi:[1,0,1] neg_lo:[1,0,0] neg_hi:[1,0,0]
	v_mul_f32_e32 v24, v24, v18
	v_mul_f32_e32 v22, v23, v18
	v_bfe_u32 v25, v24, 16, 1
	v_bfe_u32 v23, v22, 16, 1
	v_add3_u32 v24, v24, v25, s15
	v_add3_u32 v22, v22, v23, s15
	ds_write_b16_d16_hi v55, v24 offset:14592
	ds_write_b16_d16_hi v56, v22 offset:14848
	v_pk_fma_f32 v[22:23], v[40:41], s[22:23], v[30:31] op_sel_hi:[1,0,1] neg_lo:[1,0,0] neg_hi:[1,0,0]
	s_nop 0
	v_mul_f32_e32 v22, v23, v18
	v_bfe_u32 v23, v22, 16, 1
	v_add3_u32 v22, v22, v23, s15
	ds_write_b16_d16_hi v54, v22 offset:15104
	v_fma_f32 v22, v26, v18, v215
	v_cvt_pk_bf16_f32 v22, v22, v22
	ds_write_b16 v53, v22 offset:15360
	v_sub_f32_e32 v22, v20, v39
	v_pk_fma_f32 v[20:21], v[40:41], s[22:23], v[20:21] op_sel_hi:[1,0,1] neg_lo:[1,0,0] neg_hi:[1,0,0]
	v_mul_f32_e32 v22, v22, v18
	v_mul_f32_e32 v20, v21, v18
	v_mul_f32_e32 v18, v19, v18
	v_bfe_u32 v23, v22, 16, 1
	v_bfe_u32 v21, v20, 16, 1
	v_bfe_u32 v19, v18, 16, 1
	v_add3_u32 v22, v22, v23, s15
	v_add3_u32 v20, v20, v21, s15
	v_add3_u32 v18, v18, v19, s15
	ds_write_b16_d16_hi v51, v22 offset:15616
	ds_write_b16_d16_hi v49, v20 offset:15872
	ds_write_b16_d16_hi v45, v18 offset:16128
	v_lshrrev_b32_e32 v18, 1, v43
	v_and_b32_e32 v18, 32, v18
	v_lshl_or_b32 v132, v44, 6, v18
	v_or_b32_e32 v18, v132, v134
	v_lshl_add_u32 v131, v18, 8, 32
	v_bitop3_b32 v18, v42, v133, 1 bitop3:0x6c
	v_lshl_add_u32 v18, v18, 4, v131
	v_and_b32_e32 v215, 31, v0
	v_add_u32_e32 v215, s3, v215
	v_lshlrev_b32_e32 v215, 12, v215
	v_and_b32_e32 v245, 0x1c0, v0
	v_add_u32_e32 v215, v215, v245
	v_bfe_u32 v245, v0, 5, 1
	v_lshl_add_u32 v245, v245, 3, v215
	v_bfe_u32 v215, v0, 5, 1
	v_lshl_add_u32 v215, v215, 3, v245
	global_load_dwordx4 v[216:219], v215, s[60:61] offset:3072
	global_load_dwordx4 v[220:223], v215, s[60:61] offset:3104
	s_add_u32 s98, s60, 0x20000
	s_addc_u32 s99, s61, 0
	global_load_dwordx4 v[224:227], v215, s[98:99] offset:3072
	global_load_dwordx4 v[228:231], v215, s[98:99] offset:3104
	s_add_u32 s100, s60, 0x40000
	s_addc_u32 s101, s61, 0
	global_load_dwordx4 v[232:235], v215, s[100:101] offset:3072
	global_load_dwordx4 v[236:239], v215, s[100:101] offset:3104
	s_add_u32 s98, s60, 0x60000
	s_addc_u32 s99, s61, 0
	global_load_dwordx4 v[252:255], v215, s[98:99] offset:3072
	global_load_dwordx2 v[240:241], v245, s[98:99] offset:3104
	global_load_dwordx2 v[246:247], v245, s[98:99] offset:3120
	s_waitcnt lgkmcnt(0)
	s_barrier
	ds_read_b128 v[136:139], v18 offset:55296
	s_waitcnt lgkmcnt(0)
	v_mfma_f32_32x32x16_bf16 v[50:65], v[136:139], v[2:5], 0
	v_mfma_f32_32x32x16_bf16 v[34:49], v[136:139], v[6:9], 0
	v_mfma_f32_32x32x16_bf16 v[18:33], v[136:139], v[10:13], 0
	v_mfma_f32_32x32x16_bf16 v[2:17], v[136:139], v[14:17], 0
	v_bitop3_b32 v136, v135, v133, 2 bitop3:0x36
	v_lshl_add_u32 v136, v136, 4, v131
	ds_read_b128 v[136:139], v136 offset:55296
	s_waitcnt lgkmcnt(0)
	v_mfma_f32_32x32x16_bf16 v[50:65], v[136:139], v[114:117], v[50:65]
	v_bitop3_b32 v114, v135, v133, 4 bitop3:0x36
	v_lshl_add_u32 v114, v114, 4, v131
	ds_read_b128 v[114:117], v114 offset:55296
	v_mfma_f32_32x32x16_bf16 v[34:49], v[136:139], v[118:121], v[34:49]
	v_mfma_f32_32x32x16_bf16 v[18:33], v[136:139], v[122:125], v[18:33]
	s_waitcnt lgkmcnt(0)
	v_mfma_f32_32x32x16_bf16 v[34:49], v[114:117], v[102:105], v[34:49]
	v_bitop3_b32 v102, v135, v133, 6 bitop3:0x36
	v_lshl_add_u32 v102, v102, 4, v131
	ds_read_b128 v[102:105], v102 offset:55296
	v_mfma_f32_32x32x16_bf16 v[2:17], v[136:139], v[126:129], v[2:17]
	v_mfma_f32_32x32x16_bf16 v[18:33], v[114:117], v[106:109], v[18:33]
	s_waitcnt lgkmcnt(0)
	v_mfma_f32_32x32x16_bf16 v[34:49], v[102:105], v[90:93], v[34:49]
	v_bitop3_b32 v90, v135, v133, 8 bitop3:0x36
	v_lshl_add_u32 v90, v90, 4, v131
	ds_read_b128 v[90:93], v90 offset:55296
	v_mfma_f32_32x32x16_bf16 v[2:17], v[114:117], v[110:113], v[2:17]
	v_mfma_f32_32x32x16_bf16 v[18:33], v[102:105], v[94:97], v[18:33]
	v_mfma_f32_32x32x16_bf16 v[2:17], v[102:105], v[98:101], v[2:17]
	v_lshlrev_b32_e32 v104, 7, v130
	v_or_b32_e32 v102, v104, v134
	v_ashrrev_i32_e32 v103, 31, v102
	v_lshlrev_b64 v[106:107], 2, v[102:103]
	v_lshl_or_b32 v98, v135, 2, v132
	v_or_b32_e32 v100, s3, v134
	v_mov_b32_e32 v101, s5
	s_waitcnt lgkmcnt(0)
	v_mfma_f32_32x32x16_bf16 v[18:33], v[90:93], v[82:85], v[18:33]
	v_bitop3_b32 v82, v135, v133, 10 bitop3:0x36
	v_lshl_add_u32 v82, v82, 4, v131
	ds_read_b128 v[82:85], v82 offset:55296
	v_lshl_add_u64 v[108:109], s[6:7], 0, v[106:107]
	v_lshl_add_u64 v[106:107], s[92:93], 0, v[106:107]
	v_ashrrev_i32_e32 v99, 31, v98
	v_lshlrev_b64 v[98:99], 1, v[98:99]
	v_mfma_f32_32x32x16_bf16 v[2:17], v[90:93], v[86:89], v[2:17]
	s_add_i32 s3, s3, s18
	s_cmpk_gt_i32 s4, 0x7f
	s_waitcnt lgkmcnt(0)
	v_mfma_f32_32x32x16_bf16 v[18:33], v[82:85], v[74:77], v[18:33]
	v_bitop3_b32 v74, v135, v133, 12 bitop3:0x36
	v_lshl_add_u32 v74, v74, 4, v131
	ds_read_b128 v[74:77], v74 offset:55296
	v_mfma_f32_32x32x16_bf16 v[2:17], v[82:85], v[78:81], v[2:17]
	s_waitcnt lgkmcnt(0)
	v_mfma_f32_32x32x16_bf16 v[2:17], v[74:77], v[70:73], v[2:17]
	v_bitop3_b32 v70, v135, v133, 14 bitop3:0x36
	v_lshl_add_u32 v70, v70, 4, v131
	ds_read_b128 v[70:73], v70 offset:55296
	v_ashrrev_i32_e32 v133, 31, v132
	s_waitcnt lgkmcnt(0)
	v_mfma_f32_32x32x16_bf16 v[2:17], v[70:73], v[66:69], v[2:17]
	v_lshlrev_b64 v[66:67], 2, v[132:133]
	v_lshl_add_u64 v[68:69], s[10:11], 0, v[66:67]
	v_lshl_add_u64 v[66:67], s[36:37], 0, v[66:67]
	v_lshl_add_u64 v[68:69], v[68:69], 0, v[154:155]
	v_lshl_add_u64 v[70:71], v[66:67], 0, v[154:155]
	global_load_dwordx4 v[90:93], v[68:69], off
	global_load_dwordx4 v[94:97], v[70:71], off
	global_load_dwordx4 v[82:85], v[68:69], off offset:32
	global_load_dwordx4 v[86:89], v[70:71], off offset:32
	global_load_dwordx4 v[74:77], v[68:69], off offset:64
	global_load_dwordx4 v[78:81], v[70:71], off offset:64
	s_nop 0
	global_load_dwordx4 v[66:69], v[68:69], off offset:96
	s_nop 0
	global_load_dwordx4 v[70:73], v[70:71], off offset:96
	s_nop 0
	global_load_dword v118, v[108:109], off
	global_load_dword v119, v[108:109], off offset:128
	global_load_dword v120, v[108:109], off offset:256
	global_load_dword v121, v[108:109], off offset:384
	global_load_dword v122, v[106:107], off
	global_load_dword v123, v[106:107], off offset:128
	global_load_dword v124, v[106:107], off offset:256
	global_load_dword v125, v[106:107], off offset:384
	v_lshlrev_b64 v[110:111], 11, v[100:101]
	v_lshl_add_u64 v[110:111], s[62:63], 0, v[110:111]
	v_lshl_add_u64 v[110:111], v[110:111], 0, v[98:99]
	v_add_co_u32_e32 v112, vcc, 0x10000, v110
	s_nop 1
	v_addc_co_u32_e32 v113, vcc, 0, v111, vcc
	v_add_co_u32_e32 v114, vcc, 0x20000, v110
	s_nop 1
	v_addc_co_u32_e32 v115, vcc, 0, v111, vcc
	v_add_co_u32_e32 v116, vcc, 0x30000, v110
	s_nop 1
	v_addc_co_u32_e32 v117, vcc, 0, v111, vcc
	v_and_b32_e32 v126, 31, v0
	v_lshlrev_b32_e32 v136, 6, v126
	v_bfe_u32 v127, v0, 5, 1
	v_lshl_add_u32 v136, v127, 3, v136
	v_lshrrev_b32_e32 v134, 6, v0
	v_lshl_add_u32 v136, v134, 13, v136
	v_add_u32_e32 v136, 0xd820, v136
	v_bfe_u32 v126, v0, 1, 2
	v_xor_b32_e32 v127, 0, v126
	v_lshl_add_u32 v128, v127, 4, v136
	v_xor_b32_e32 v127, 1, v126
	v_lshl_add_u32 v129, v127, 4, v136
	v_xor_b32_e32 v127, 2, v126
	v_lshl_add_u32 v130, v127, 4, v136
	v_xor_b32_e32 v127, 3, v126
	v_lshl_add_u32 v131, v127, 4, v136
	v_bfe_u32 v135, v0, 2, 4
	v_lshlrev_b32_e32 v132, 6, v135
	v_and_b32_e32 v127, 3, v0
	v_bfe_u32 v126, v0, 3, 2
	v_xor_b32_e32 v126, v127, v126
	v_lshl_add_u32 v132, v126, 4, v132
	v_lshl_add_u32 v132, v134, 13, v132
	v_add_u32_e32 v132, 0xd820, v132
	v_and_b32_e32 v133, -32, v100
	v_add_u32_e32 v133, v133, v135
	v_lshlrev_b32_e32 v133, 11, v133
	v_lshl_add_u32 v133, v134, 6, v133
	v_lshl_add_u32 v133, v127, 4, v133
	s_waitcnt vmcnt(0)
	s_nop 1
	v_permlane32_swap_b32 v216, v218
	v_permlane32_swap_b32 v217, v219
	v_permlane32_swap_b32 v220, v222
	v_permlane32_swap_b32 v221, v223
	v_permlane32_swap_b32 v224, v226
	v_permlane32_swap_b32 v225, v227
	v_permlane32_swap_b32 v228, v230
	v_permlane32_swap_b32 v229, v231
	v_permlane32_swap_b32 v232, v234
	v_permlane32_swap_b32 v233, v235
	v_permlane32_swap_b32 v236, v238
	v_permlane32_swap_b32 v237, v239
	v_permlane32_swap_b32 v252, v254
	v_permlane32_swap_b32 v253, v255
	v_mul_f32_e32 v126, v94, v118
	v_fmac_f32_e32 v126, v50, v90
	v_add_f32_e32 v50, v122, v126
	v_lshlrev_b32_e32 v127, 16, v216
	v_mul_f32_e32 v50, v50, v127
	v_mul_f32_e32 v126, v95, v118
	v_fmac_f32_e32 v126, v51, v91
	v_add_f32_e32 v51, v122, v126
	v_and_b32_e32 v127, 0xffff0000, v216
	v_mul_f32_e32 v51, v51, v127
	v_mul_f32_e32 v126, v96, v118
	v_fmac_f32_e32 v126, v52, v92
	v_add_f32_e32 v52, v122, v126
	v_lshlrev_b32_e32 v127, 16, v217
	v_mul_f32_e32 v52, v52, v127
	v_mul_f32_e32 v126, v97, v118
	v_fmac_f32_e32 v126, v53, v93
	v_add_f32_e32 v53, v122, v126
	v_and_b32_e32 v127, 0xffff0000, v217
	v_mul_f32_e32 v53, v53, v127
	v_cvt_pk_bf16_f32 v50, v50, v51
	v_cvt_pk_bf16_f32 v51, v52, v53
	ds_write_b64 v128, v[50:51] offset:0
	v_mul_f32_e32 v126, v86, v118
	v_fmac_f32_e32 v126, v54, v82
	v_add_f32_e32 v54, v122, v126
	v_lshlrev_b32_e32 v127, 16, v218
	v_mul_f32_e32 v54, v54, v127
	v_mul_f32_e32 v126, v87, v118
	v_fmac_f32_e32 v126, v55, v83
	v_add_f32_e32 v55, v122, v126
	v_and_b32_e32 v127, 0xffff0000, v218
	v_mul_f32_e32 v55, v55, v127
	v_mul_f32_e32 v126, v88, v118
	v_fmac_f32_e32 v126, v56, v84
	v_add_f32_e32 v56, v122, v126
	v_lshlrev_b32_e32 v127, 16, v219
	v_mul_f32_e32 v56, v56, v127
	v_mul_f32_e32 v126, v89, v118
	v_fmac_f32_e32 v126, v57, v85
	v_add_f32_e32 v57, v122, v126
	v_and_b32_e32 v127, 0xffff0000, v219
	v_mul_f32_e32 v57, v57, v127
	v_cvt_pk_bf16_f32 v54, v54, v55
	v_cvt_pk_bf16_f32 v55, v56, v57
	ds_write_b64 v129, v[54:55] offset:0
	v_mul_f32_e32 v126, v78, v118
	v_fmac_f32_e32 v126, v58, v74
	v_add_f32_e32 v58, v122, v126
	v_lshlrev_b32_e32 v127, 16, v220
	v_mul_f32_e32 v58, v58, v127
	v_mul_f32_e32 v126, v79, v118
	v_fmac_f32_e32 v126, v59, v75
	v_add_f32_e32 v59, v122, v126
	v_and_b32_e32 v127, 0xffff0000, v220
	v_mul_f32_e32 v59, v59, v127
	v_mul_f32_e32 v126, v80, v118
	v_fmac_f32_e32 v126, v60, v76
	v_add_f32_e32 v60, v122, v126
	v_lshlrev_b32_e32 v127, 16, v221
	v_mul_f32_e32 v60, v60, v127
	v_mul_f32_e32 v126, v81, v118
	v_fmac_f32_e32 v126, v61, v77
	v_add_f32_e32 v61, v122, v126
	v_and_b32_e32 v127, 0xffff0000, v221
	v_mul_f32_e32 v61, v61, v127
	v_cvt_pk_bf16_f32 v58, v58, v59
	v_cvt_pk_bf16_f32 v59, v60, v61
	ds_write_b64 v130, v[58:59] offset:0
	v_mul_f32_e32 v126, v70, v118
	v_fmac_f32_e32 v126, v62, v66
	v_add_f32_e32 v62, v122, v126
	v_lshlrev_b32_e32 v127, 16, v222
	v_mul_f32_e32 v62, v62, v127
	v_mul_f32_e32 v126, v71, v118
	v_fmac_f32_e32 v126, v63, v67
	v_add_f32_e32 v63, v122, v126
	v_and_b32_e32 v127, 0xffff0000, v222
	v_mul_f32_e32 v63, v63, v127
	v_mul_f32_e32 v126, v72, v118
	v_fmac_f32_e32 v126, v64, v68
	v_add_f32_e32 v64, v122, v126
	v_lshlrev_b32_e32 v127, 16, v223
	v_mul_f32_e32 v64, v64, v127
	v_mul_f32_e32 v126, v73, v118
	v_fmac_f32_e32 v126, v65, v69
	v_add_f32_e32 v65, v122, v126
	v_and_b32_e32 v127, 0xffff0000, v223
	v_mul_f32_e32 v65, v65, v127
	v_cvt_pk_bf16_f32 v62, v62, v63
	v_cvt_pk_bf16_f32 v63, v64, v65
	ds_write_b64 v131, v[62:63] offset:0
	v_mul_f32_e32 v126, v94, v119
	v_fmac_f32_e32 v126, v34, v90
	v_add_f32_e32 v34, v123, v126
	v_lshlrev_b32_e32 v127, 16, v224
	v_mul_f32_e32 v34, v34, v127
	v_mul_f32_e32 v126, v95, v119
	v_fmac_f32_e32 v126, v35, v91
	v_add_f32_e32 v35, v123, v126
	v_and_b32_e32 v127, 0xffff0000, v224
	v_mul_f32_e32 v35, v35, v127
	v_mul_f32_e32 v126, v96, v119
	v_fmac_f32_e32 v126, v36, v92
	v_add_f32_e32 v36, v123, v126
	v_lshlrev_b32_e32 v127, 16, v225
	v_mul_f32_e32 v36, v36, v127
	v_mul_f32_e32 v126, v97, v119
	v_fmac_f32_e32 v126, v37, v93
	v_add_f32_e32 v37, v123, v126
	v_and_b32_e32 v127, 0xffff0000, v225
	v_mul_f32_e32 v37, v37, v127
	v_cvt_pk_bf16_f32 v34, v34, v35
	v_cvt_pk_bf16_f32 v35, v36, v37
	ds_write_b64 v128, v[34:35] offset:2048
	v_mul_f32_e32 v126, v86, v119
	v_fmac_f32_e32 v126, v38, v82
	v_add_f32_e32 v38, v123, v126
	v_lshlrev_b32_e32 v127, 16, v226
	v_mul_f32_e32 v38, v38, v127
	v_mul_f32_e32 v126, v87, v119
	v_fmac_f32_e32 v126, v39, v83
	v_add_f32_e32 v39, v123, v126
	v_and_b32_e32 v127, 0xffff0000, v226
	v_mul_f32_e32 v39, v39, v127
	v_mul_f32_e32 v126, v88, v119
	v_fmac_f32_e32 v126, v40, v84
	v_add_f32_e32 v40, v123, v126
	v_lshlrev_b32_e32 v127, 16, v227
	v_mul_f32_e32 v40, v40, v127
	v_mul_f32_e32 v126, v89, v119
	v_fmac_f32_e32 v126, v41, v85
	v_add_f32_e32 v41, v123, v126
	v_and_b32_e32 v127, 0xffff0000, v227
	v_mul_f32_e32 v41, v41, v127
	v_cvt_pk_bf16_f32 v38, v38, v39
	v_cvt_pk_bf16_f32 v39, v40, v41
	ds_write_b64 v129, v[38:39] offset:2048
	v_mul_f32_e32 v126, v78, v119
	v_fmac_f32_e32 v126, v42, v74
	v_add_f32_e32 v42, v123, v126
	v_lshlrev_b32_e32 v127, 16, v228
	v_mul_f32_e32 v42, v42, v127
	v_mul_f32_e32 v126, v79, v119
	v_fmac_f32_e32 v126, v43, v75
	v_add_f32_e32 v43, v123, v126
	v_and_b32_e32 v127, 0xffff0000, v228
	v_mul_f32_e32 v43, v43, v127
	v_mul_f32_e32 v126, v80, v119
	v_fmac_f32_e32 v126, v44, v76
	v_add_f32_e32 v44, v123, v126
	v_lshlrev_b32_e32 v127, 16, v229
	v_mul_f32_e32 v44, v44, v127
	v_mul_f32_e32 v126, v81, v119
	v_fmac_f32_e32 v126, v45, v77
	v_add_f32_e32 v45, v123, v126
	v_and_b32_e32 v127, 0xffff0000, v229
	v_mul_f32_e32 v45, v45, v127
	v_cvt_pk_bf16_f32 v42, v42, v43
	v_cvt_pk_bf16_f32 v43, v44, v45
	ds_write_b64 v130, v[42:43] offset:2048
	v_mul_f32_e32 v126, v70, v119
	v_fmac_f32_e32 v126, v46, v66
	v_add_f32_e32 v46, v123, v126
	v_lshlrev_b32_e32 v127, 16, v230
	v_mul_f32_e32 v46, v46, v127
	v_mul_f32_e32 v126, v71, v119
	v_fmac_f32_e32 v126, v47, v67
	v_add_f32_e32 v47, v123, v126
	v_and_b32_e32 v127, 0xffff0000, v230
	v_mul_f32_e32 v47, v47, v127
	v_mul_f32_e32 v126, v72, v119
	v_fmac_f32_e32 v126, v48, v68
	v_add_f32_e32 v48, v123, v126
	v_lshlrev_b32_e32 v127, 16, v231
	v_mul_f32_e32 v48, v48, v127
	v_mul_f32_e32 v126, v73, v119
	v_fmac_f32_e32 v126, v49, v69
	v_add_f32_e32 v49, v123, v126
	v_and_b32_e32 v127, 0xffff0000, v231
	v_mul_f32_e32 v49, v49, v127
	v_cvt_pk_bf16_f32 v46, v46, v47
	v_cvt_pk_bf16_f32 v47, v48, v49
	ds_write_b64 v131, v[46:47] offset:2048
	v_mul_f32_e32 v126, v94, v120
	v_fmac_f32_e32 v126, v18, v90
	v_add_f32_e32 v18, v124, v126
	v_lshlrev_b32_e32 v127, 16, v232
	v_mul_f32_e32 v18, v18, v127
	v_mul_f32_e32 v126, v95, v120
	v_fmac_f32_e32 v126, v19, v91
	v_add_f32_e32 v19, v124, v126
	v_and_b32_e32 v127, 0xffff0000, v232
	v_mul_f32_e32 v19, v19, v127
	v_mul_f32_e32 v126, v96, v120
	v_fmac_f32_e32 v126, v20, v92
	v_add_f32_e32 v20, v124, v126
	v_lshlrev_b32_e32 v127, 16, v233
	v_mul_f32_e32 v20, v20, v127
	v_mul_f32_e32 v126, v97, v120
	v_fmac_f32_e32 v126, v21, v93
	v_add_f32_e32 v21, v124, v126
	v_and_b32_e32 v127, 0xffff0000, v233
	v_mul_f32_e32 v21, v21, v127
	v_cvt_pk_bf16_f32 v18, v18, v19
	v_cvt_pk_bf16_f32 v19, v20, v21
	ds_write_b64 v128, v[18:19] offset:4096
	v_mul_f32_e32 v126, v86, v120
	v_fmac_f32_e32 v126, v22, v82
	v_add_f32_e32 v22, v124, v126
	v_lshlrev_b32_e32 v127, 16, v234
	v_mul_f32_e32 v22, v22, v127
	v_mul_f32_e32 v126, v87, v120
	v_fmac_f32_e32 v126, v23, v83
	v_add_f32_e32 v23, v124, v126
	v_and_b32_e32 v127, 0xffff0000, v234
	v_mul_f32_e32 v23, v23, v127
	v_mul_f32_e32 v126, v88, v120
	v_fmac_f32_e32 v126, v24, v84
	v_add_f32_e32 v24, v124, v126
	v_lshlrev_b32_e32 v127, 16, v235
	v_mul_f32_e32 v24, v24, v127
	v_mul_f32_e32 v126, v89, v120
	v_fmac_f32_e32 v126, v25, v85
	v_add_f32_e32 v25, v124, v126
	v_and_b32_e32 v127, 0xffff0000, v235
	v_mul_f32_e32 v25, v25, v127
	v_cvt_pk_bf16_f32 v22, v22, v23
	v_cvt_pk_bf16_f32 v23, v24, v25
	ds_write_b64 v129, v[22:23] offset:4096
	v_mul_f32_e32 v126, v78, v120
	v_fmac_f32_e32 v126, v26, v74
	v_add_f32_e32 v26, v124, v126
	v_lshlrev_b32_e32 v127, 16, v236
	v_mul_f32_e32 v26, v26, v127
	v_mul_f32_e32 v126, v79, v120
	v_fmac_f32_e32 v126, v27, v75
	v_add_f32_e32 v27, v124, v126
	v_and_b32_e32 v127, 0xffff0000, v236
	v_mul_f32_e32 v27, v27, v127
	v_mul_f32_e32 v126, v80, v120
	v_fmac_f32_e32 v126, v28, v76
	v_add_f32_e32 v28, v124, v126
	v_lshlrev_b32_e32 v127, 16, v237
	v_mul_f32_e32 v28, v28, v127
	v_mul_f32_e32 v126, v81, v120
	v_fmac_f32_e32 v126, v29, v77
	v_add_f32_e32 v29, v124, v126
	v_and_b32_e32 v127, 0xffff0000, v237
	v_mul_f32_e32 v29, v29, v127
	v_cvt_pk_bf16_f32 v26, v26, v27
	v_cvt_pk_bf16_f32 v27, v28, v29
	ds_write_b64 v130, v[26:27] offset:4096
	v_mul_f32_e32 v126, v70, v120
	v_fmac_f32_e32 v126, v30, v66
	v_add_f32_e32 v30, v124, v126
	v_lshlrev_b32_e32 v127, 16, v238
	v_mul_f32_e32 v30, v30, v127
	v_mul_f32_e32 v126, v71, v120
	v_fmac_f32_e32 v126, v31, v67
	v_add_f32_e32 v31, v124, v126
	v_and_b32_e32 v127, 0xffff0000, v238
	v_mul_f32_e32 v31, v31, v127
	v_mul_f32_e32 v126, v72, v120
	v_fmac_f32_e32 v126, v32, v68
	v_add_f32_e32 v32, v124, v126
	v_lshlrev_b32_e32 v127, 16, v239
	v_mul_f32_e32 v32, v32, v127
	v_mul_f32_e32 v126, v73, v120
	v_fmac_f32_e32 v126, v33, v69
	v_add_f32_e32 v33, v124, v126
	v_and_b32_e32 v127, 0xffff0000, v239
	v_mul_f32_e32 v33, v33, v127
	v_cvt_pk_bf16_f32 v30, v30, v31
	v_cvt_pk_bf16_f32 v31, v32, v33
	ds_write_b64 v131, v[30:31] offset:4096
	v_mul_f32_e32 v126, v94, v121
	v_fmac_f32_e32 v126, v2, v90
	v_add_f32_e32 v2, v125, v126
	v_lshlrev_b32_e32 v127, 16, v252
	v_mul_f32_e32 v2, v2, v127
	v_mul_f32_e32 v126, v95, v121
	v_fmac_f32_e32 v126, v3, v91
	v_add_f32_e32 v3, v125, v126
	v_and_b32_e32 v127, 0xffff0000, v252
	v_mul_f32_e32 v3, v3, v127
	v_mul_f32_e32 v126, v96, v121
	v_fmac_f32_e32 v126, v4, v92
	v_add_f32_e32 v4, v125, v126
	v_lshlrev_b32_e32 v127, 16, v253
	v_mul_f32_e32 v4, v4, v127
	v_mul_f32_e32 v126, v97, v121
	v_fmac_f32_e32 v126, v5, v93
	v_add_f32_e32 v5, v125, v126
	v_and_b32_e32 v127, 0xffff0000, v253
	v_mul_f32_e32 v5, v5, v127
	v_cvt_pk_bf16_f32 v2, v2, v3
	v_cvt_pk_bf16_f32 v3, v4, v5
	ds_write_b64 v128, v[2:3] offset:6144
	v_mul_f32_e32 v126, v86, v121
	v_fmac_f32_e32 v126, v6, v82
	v_add_f32_e32 v6, v125, v126
	v_lshlrev_b32_e32 v127, 16, v254
	v_mul_f32_e32 v6, v6, v127
	v_mul_f32_e32 v126, v87, v121
	v_fmac_f32_e32 v126, v7, v83
	v_add_f32_e32 v7, v125, v126
	v_and_b32_e32 v127, 0xffff0000, v254
	v_mul_f32_e32 v7, v7, v127
	v_mul_f32_e32 v126, v88, v121
	v_fmac_f32_e32 v126, v8, v84
	v_add_f32_e32 v8, v125, v126
	v_lshlrev_b32_e32 v127, 16, v255
	v_mul_f32_e32 v8, v8, v127
	v_mul_f32_e32 v126, v89, v121
	v_fmac_f32_e32 v126, v9, v85
	v_add_f32_e32 v9, v125, v126
	v_and_b32_e32 v127, 0xffff0000, v255
	v_mul_f32_e32 v9, v9, v127
	v_cvt_pk_bf16_f32 v6, v6, v7
	v_cvt_pk_bf16_f32 v7, v8, v9
	ds_write_b64 v129, v[6:7] offset:6144
	v_mul_f32_e32 v126, v78, v121
	v_fmac_f32_e32 v126, v10, v74
	v_add_f32_e32 v10, v125, v126
	v_lshlrev_b32_e32 v127, 16, v240
	v_mul_f32_e32 v10, v10, v127
	v_mul_f32_e32 v126, v79, v121
	v_fmac_f32_e32 v126, v11, v75
	v_add_f32_e32 v11, v125, v126
	v_and_b32_e32 v127, 0xffff0000, v240
	v_mul_f32_e32 v11, v11, v127
	v_mul_f32_e32 v126, v80, v121
	v_fmac_f32_e32 v126, v12, v76
	v_add_f32_e32 v12, v125, v126
	v_lshlrev_b32_e32 v127, 16, v241
	v_mul_f32_e32 v12, v12, v127
	v_mul_f32_e32 v126, v81, v121
	v_fmac_f32_e32 v126, v13, v77
	v_add_f32_e32 v13, v125, v126
	v_and_b32_e32 v127, 0xffff0000, v241
	v_mul_f32_e32 v13, v13, v127
	v_cvt_pk_bf16_f32 v10, v10, v11
	v_cvt_pk_bf16_f32 v11, v12, v13
	ds_write_b64 v130, v[10:11] offset:6144
	v_mul_f32_e32 v126, v70, v121
	v_fmac_f32_e32 v126, v14, v66
	v_add_f32_e32 v14, v125, v126
	v_lshlrev_b32_e32 v127, 16, v246
	v_mul_f32_e32 v14, v14, v127
	v_mul_f32_e32 v126, v71, v121
	v_fmac_f32_e32 v126, v15, v67
	v_add_f32_e32 v15, v125, v126
	v_and_b32_e32 v127, 0xffff0000, v246
	v_mul_f32_e32 v15, v15, v127
	v_mul_f32_e32 v126, v72, v121
	v_fmac_f32_e32 v126, v16, v68
	v_add_f32_e32 v16, v125, v126
	v_lshlrev_b32_e32 v127, 16, v247
	v_mul_f32_e32 v16, v16, v127
	v_mul_f32_e32 v126, v73, v121
	v_fmac_f32_e32 v126, v17, v69
	v_add_f32_e32 v17, v125, v126
	v_and_b32_e32 v127, 0xffff0000, v247
	v_mul_f32_e32 v17, v17, v127
	v_cvt_pk_bf16_f32 v14, v14, v15
	v_cvt_pk_bf16_f32 v15, v16, v17
	ds_write_b64 v131, v[14:15] offset:6144
	s_waitcnt lgkmcnt(0)
	ds_read_b128 v[2:5], v132 offset:0
	ds_read_b128 v[6:9], v132 offset:1024
	ds_read_b128 v[10:13], v132 offset:2048
	ds_read_b128 v[14:17], v132 offset:3072
	ds_read_b128 v[18:21], v132 offset:4096
	ds_read_b128 v[22:25], v132 offset:5120
	ds_read_b128 v[26:29], v132 offset:6144
	ds_read_b128 v[30:33], v132 offset:7168
	s_waitcnt lgkmcnt(7)
	global_store_dwordx4 v133, v[2:5], s[62:63] offset:1536
	v_add_u32_e32 v127, 0x8000, v133
	s_waitcnt lgkmcnt(6)
	global_store_dwordx4 v127, v[6:9], s[62:63] offset:1536
	v_add_u32_e32 v126, 0x10000, v133
	s_waitcnt lgkmcnt(5)
	global_store_dwordx4 v126, v[10:13], s[62:63] offset:1536
	v_add_u32_e32 v127, 0x18000, v133
	s_waitcnt lgkmcnt(4)
	global_store_dwordx4 v127, v[14:17], s[62:63] offset:1536
	v_add_u32_e32 v126, 0x20000, v133
	s_waitcnt lgkmcnt(3)
	global_store_dwordx4 v126, v[18:21], s[62:63] offset:1536
	v_add_u32_e32 v127, 0x28000, v133
	s_waitcnt lgkmcnt(2)
	global_store_dwordx4 v127, v[22:25], s[62:63] offset:1536
	v_add_u32_e32 v126, 0x30000, v133
	s_waitcnt lgkmcnt(1)
	global_store_dwordx4 v126, v[26:29], s[62:63] offset:1536
	v_add_u32_e32 v127, 0x38000, v133
	s_waitcnt lgkmcnt(0)
	global_store_dwordx4 v127, v[30:33], s[62:63] offset:1536
	s_barrier
	s_cbranch_scc0 .LBB0_849
